# prep token loop: a0/w0 pre-scaled by -log2e once per pass (add+mul -> one fmamk), two constant multiplies merged: 12 fewer VALU ops per token
# speedup vs baseline: 1.0108x; 1.0039x over previous
.LBB0_485:
	s_or_b64 exec, exec, s[6:7]
	v_lshl_add_u32 v0, s0, 8, v32
	v_readlane_b32 s60, v253, 46
	v_ashrrev_i32_e32 v1, 31, v0
	v_readlane_b32 s61, v253, 47
	v_readlane_b32 s62, v253, 48
	v_readlane_b32 s63, v253, 49
	v_readlane_b32 s64, v253, 50
	v_readlane_b32 s65, v253, 51
	v_readlane_b32 s66, v253, 52
	v_readlane_b32 s67, v253, 53
	v_lshlrev_b64 v[2:3], 2, v[0:1]
	v_readlane_b32 s52, v253, 62
	v_lshl_add_u32 v0, s0, 9, v0
	v_readlane_b32 s70, v253, 56
	v_readlane_b32 s71, v253, 57
	v_readlane_b32 s74, v253, 60
	v_readlane_b32 s75, v253, 61
	v_readlane_b32 s54, v254, 0
	v_readlane_b32 s55, v254, 1
	v_ashrrev_i32_e32 v1, 31, v0
	v_lshl_add_u64 v[4:5], s[74:75], 0, v[2:3]
	v_lshl_add_u64 v[2:3], s[54:55], 0, v[2:3]
	s_mul_i32 s1, s0, 0x300
	v_lshl_add_u64 v[0:1], v[0:1], 2, s[70:71]
	v_readfirstlane_b32 s82, v160
	s_lshr_b32 s82, s82, 6
	s_lshl_b32 s82, s82, 10
	s_add_i32 s82, s82, 0xd000
	v_add_u32_e32 v249, s82, v251
	ds_write_b128 v249, v[222:225]
	s_waitcnt lgkmcnt(0)
	s_barrier
	s_xor_b64 s[18:19], s[16:17], -1
	v_readlane_b32 s22, v254, 34
	v_readlane_b32 s72, v254, 43
	v_readlane_b32 s73, v254, 44
	v_readlane_b32 s92, v254, 49
	v_readfirstlane_b32 s0, v160
	s_lshr_b32 s0, s0, 6
	s_and_b32 s0, s0, 3
	s_mul_i32 s53, s51, 20
	s_add_i32 s53, s53, s0
	s_lshl_b32 s0, s0, 10
	s_add_i32 s92, s92, s0
	v_and_b32_e32 v250, 63, v160
	v_lshlrev_b32_e32 v251, 4, v250
	v_lshlrev_b32_e32 v250, 3, v250
	v_add_u32_e32 v31, s92, v251
	s_add_u32 s28, s72, 0x664a000
	s_addc_u32 s29, s73, 0
	s_add_u32 s34, s72, 0xaeca000
	s_addc_u32 s35, s73, 0
	s_add_u32 s42, s72, 0x13aca000
	s_addc_u32 s43, s73, 0
	s_waitcnt lgkmcnt(0)
	s_cmp_eq_u64 s[16:17], 0
	s_cbranch_scc1 .Lprep_tok_d1
	ds_read_b128 v[210:213], v251 offset:53248
	ds_read_b128 v[214:217], v251 offset:54272
	ds_read_b128 v[218:221], v251 offset:55296
	ds_read_b128 v[198:201], v251 offset:56320
	ds_read_b128 v[194:197], v251 offset:57344
	ds_read_b128 v[190:193], v251 offset:58368
	ds_read_b128 v[202:205], v251 offset:59392
	ds_read_b128 v[206:209], v251 offset:60416
	s_add_i32 s56, s53, 0
	s_cmpk_lt_i32 s56, 0x2000
	s_movk_i32 s0, 0x3ff
	s_cselect_b32 s0, 0xff, s0
	s_and_b32 s1, s56, s0
	s_cmp_lg_u32 s1, 0
	s_cselect_b32 s59, 1.0, 0
	s_cselect_b32 s1, -1, 0
	s_add_i32 s1, s56, s1
	s_mul_i32 s0, s56, 0x1d00
	s_add_u32 s76, s28, s0
	s_addc_u32 s77, s29, 0
	s_mul_i32 s0, s1, 0x1d00
	s_add_u32 s78, s28, s0
	s_addc_u32 s79, s29, 0
	global_load_dwordx2 v[222:223], v250, s[76:77] offset:0
	global_load_dwordx2 v[224:225], v250, s[76:77] offset:512
	global_load_dwordx2 v[226:227], v250, s[76:77] offset:1024
	global_load_dwordx2 v[228:229], v250, s[78:79] offset:0
	global_load_dwordx2 v[230:231], v250, s[78:79] offset:512
	global_load_dwordx2 v[232:233], v250, s[78:79] offset:1024
	s_add_i32 s57, s53, 4
	s_cmpk_lt_i32 s57, 0x2000
	s_movk_i32 s0, 0x3ff
	s_cselect_b32 s0, 0xff, s0
	s_and_b32 s1, s57, s0
	s_cmp_lg_u32 s1, 0
	s_cselect_b32 s60, 1.0, 0
	s_cselect_b32 s1, -1, 0
	s_add_i32 s1, s57, s1
	s_mul_i32 s0, s57, 0x1d00
	s_add_u32 s80, s28, s0
	s_addc_u32 s81, s29, 0
	s_mul_i32 s0, s1, 0x1d00
	s_add_u32 s82, s28, s0
	s_addc_u32 s83, s29, 0
	global_load_dwordx2 v[236:237], v250, s[80:81] offset:0
	global_load_dwordx2 v[238:239], v250, s[80:81] offset:512
	global_load_dwordx2 v[240:241], v250, s[80:81] offset:1024
	global_load_dwordx2 v[242:243], v250, s[82:83] offset:0
	global_load_dwordx2 v[244:245], v250, s[82:83] offset:512
	global_load_dwordx2 v[246:247], v250, s[82:83] offset:1024
	s_add_i32 s58, s53, 8
	s_cmpk_lt_i32 s58, 0x2000
	s_movk_i32 s0, 0x3ff
	s_cselect_b32 s0, 0xff, s0
	s_and_b32 s1, s58, s0
	s_cmp_lg_u32 s1, 0
	s_cselect_b32 s61, 1.0, 0
	s_cselect_b32 s1, -1, 0
	s_add_i32 s1, s58, s1
	s_mul_i32 s0, s58, 0x1d00
	s_add_u32 s84, s28, s0
	s_addc_u32 s85, s29, 0
	s_mul_i32 s0, s1, 0x1d00
	s_add_u32 s96, s28, s0
	s_addc_u32 s97, s29, 0
	global_load_dwordx2 v[0:1], v250, s[84:85] offset:0
	global_load_dwordx2 v[2:3], v250, s[84:85] offset:512
	global_load_dwordx2 v[4:5], v250, s[84:85] offset:1024
	global_load_dwordx2 v[6:7], v250, s[96:97] offset:0
	global_load_dwordx2 v[8:9], v250, s[96:97] offset:512
	global_load_dwordx2 v[10:11], v250, s[96:97] offset:1024
	ds_read_b128 v[14:17], v31 offset:0
	ds_read_b128 v[18:21], v31 offset:20480
	ds_read_b128 v[22:25], v31 offset:4096
	ds_read_b128 v[26:29], v31 offset:24576
	s_waitcnt lgkmcnt(4)
	s_waitcnt vmcnt(12)
	v_lshlrev_b32_e32 v134, 16, v222
	v_and_b32_e32 v222, 0xffff0000, v222
	v_lshlrev_b32_e32 v135, 16, v223
	v_and_b32_e32 v223, 0xffff0000, v223
	v_lshlrev_b32_e32 v136, 16, v224
	v_and_b32_e32 v224, 0xffff0000, v224
	v_lshlrev_b32_e32 v137, 16, v225
	v_and_b32_e32 v225, 0xffff0000, v225
	v_lshlrev_b32_e32 v138, 16, v226
	v_and_b32_e32 v226, 0xffff0000, v226
	v_lshlrev_b32_e32 v139, 16, v227
	v_and_b32_e32 v227, 0xffff0000, v227
	v_lshlrev_b32_e32 v140, 16, v228
	v_and_b32_e32 v228, 0xffff0000, v228
	v_lshlrev_b32_e32 v141, 16, v229
	v_and_b32_e32 v229, 0xffff0000, v229
	v_lshlrev_b32_e32 v142, 16, v230
	v_and_b32_e32 v230, 0xffff0000, v230
	v_lshlrev_b32_e32 v143, 16, v231
	v_and_b32_e32 v231, 0xffff0000, v231
	v_lshlrev_b32_e32 v144, 16, v232
	v_and_b32_e32 v232, 0xffff0000, v232
	v_lshlrev_b32_e32 v145, 16, v233
	v_and_b32_e32 v233, 0xffff0000, v233
	v_fma_f32 v140, s59, v140, -v134
	v_fma_f32 v228, s59, v228, -v222
	v_fma_f32 v141, s59, v141, -v135
	v_fma_f32 v229, s59, v229, -v223
	v_fmac_f32_e32 v134, v210, v140
	v_fmac_f32_e32 v222, v211, v228
	v_fmac_f32_e32 v135, v212, v141
	v_fmac_f32_e32 v223, v213, v229
	v_fma_f32 v142, s59, v142, -v136
	v_fma_f32 v230, s59, v230, -v224
	v_fma_f32 v143, s59, v143, -v137
	v_fma_f32 v231, s59, v231, -v225
	v_fmac_f32_e32 v136, v214, v142
	v_fmac_f32_e32 v224, v215, v230
	v_fmac_f32_e32 v137, v216, v143
	v_fmac_f32_e32 v225, v217, v231
	v_fma_f32 v144, s59, v144, -v138
	v_fma_f32 v232, s59, v232, -v226
	v_fma_f32 v145, s59, v145, -v139
	v_fma_f32 v233, s59, v233, -v227
	v_fmac_f32_e32 v138, v218, v144
	v_fmac_f32_e32 v226, v219, v232
	v_fmac_f32_e32 v139, v220, v145
	v_fmac_f32_e32 v227, v221, v233
	v_mul_f32_e32 v148, v198, v136
	v_mul_f32_e32 v149, v199, v224
	v_mul_f32_e32 v150, v200, v137
	v_mul_f32_e32 v151, v201, v225
	v_mul_f32_e32 v176, v148, v148
	v_fmac_f32_e32 v176, v149, v149
	v_fmac_f32_e32 v176, v150, v150
	v_fmac_f32_e32 v176, v151, v151
	s_waitcnt lgkmcnt(2)
	v_mul_f32_e32 v194, 0xbfb8aa3b, v194
	v_mul_f32_e32 v195, 0xbfb8aa3b, v195
	v_mul_f32_e32 v196, 0xbfb8aa3b, v196
	v_mul_f32_e32 v197, 0xbfb8aa3b, v197
	v_mul_f32_e32 v190, 0xbfb8aa3b, v190
	v_mul_f32_e32 v191, 0xbfb8aa3b, v191
	v_mul_f32_e32 v192, 0xbfb8aa3b, v192
	v_mul_f32_e32 v193, 0xbfb8aa3b, v193
	v_fmamk_f32 v18, v18, 0xbfb8aa3b, v194
	v_fmamk_f32 v19, v19, 0xbfb8aa3b, v195
	v_fmamk_f32 v20, v20, 0xbfb8aa3b, v196
	v_fmamk_f32 v21, v21, 0xbfb8aa3b, v197
	v_add_f32_dpp v176, v176, v176 quad_perm:[1,0,3,2] row_mask:0xf bank_mask:0xf bound_ctrl:1
	v_exp_f32_e32 v18, v18
	v_exp_f32_e32 v19, v19
	v_exp_f32_e32 v20, v20
	v_exp_f32_e32 v21, v21
	v_add_f32_dpp v176, v176, v176 quad_perm:[2,3,0,1] row_mask:0xf bank_mask:0xf bound_ctrl:1
	v_add_f32_e32 v18, 1.0, v18
	v_add_f32_e32 v19, 1.0, v19
	v_add_f32_e32 v20, 1.0, v20
	v_add_f32_e32 v21, 1.0, v21
	v_add_f32_dpp v176, v176, v176 row_half_mirror row_mask:0xf bank_mask:0xf bound_ctrl:1
	v_rcp_f32_e32 v18, v18
	v_rcp_f32_e32 v19, v19
	v_rcp_f32_e32 v20, v20
	v_rcp_f32_e32 v21, v21
	v_add_f32_dpp v176, v176, v176 row_mirror row_mask:0xf bank_mask:0xf bound_ctrl:1
	v_fmamk_f32 v14, v14, 0xbfb8aa3b, v190
	v_fmamk_f32 v15, v15, 0xbfb8aa3b, v191
	v_fmamk_f32 v16, v16, 0xbfb8aa3b, v192
	v_fmamk_f32 v17, v17, 0xbfb8aa3b, v193
	v_sqrt_f32_e32 v176, v176
	v_exp_f32_e32 v14, v14
	v_exp_f32_e32 v15, v15
	v_exp_f32_e32 v16, v16
	v_exp_f32_e32 v17, v17
	v_max_f32_e32 v176, 0x2b8cbccc, v176
	v_add_f32_e32 v14, 1.0, v14
	v_add_f32_e32 v15, 1.0, v15
	v_add_f32_e32 v16, 1.0, v16
	v_add_f32_e32 v17, 1.0, v17
	v_rcp_f32_e32 v178, v176
	v_rcp_f32_e32 v14, v14
	v_rcp_f32_e32 v15, v15
	v_rcp_f32_e32 v16, v16
	v_rcp_f32_e32 v17, v17
	v_mul_f32_e32 v14, 0xbf60028a, v14
	v_mul_f32_e32 v15, 0xbf60028a, v15
	v_mul_f32_e32 v16, 0xbf60028a, v16
	v_mul_f32_e32 v17, 0xbf60028a, v17
	v_exp_f32_e32 v14, v14
	v_exp_f32_e32 v15, v15
	v_exp_f32_e32 v16, v16
	v_exp_f32_e32 v17, v17
	v_add_f32_e32 v152, -1.0, v18
	v_add_f32_e32 v153, -1.0, v19
	v_add_f32_e32 v154, -1.0, v20
	v_add_f32_e32 v155, -1.0, v21
	v_fma_f32 v152, v202, v152, 1.0
	v_fma_f32 v153, v203, v153, 1.0
	v_fma_f32 v154, v204, v154, 1.0
	v_fma_f32 v155, v205, v155, 1.0
	v_mul_f32_e32 v152, v136, v152
	v_mul_f32_e32 v153, v224, v153
	v_mul_f32_e32 v154, v137, v154
	v_mul_f32_e32 v155, v225, v155
	v_mul_f32_e32 v156, v134, v152
	v_mul_f32_e32 v157, v222, v153
	v_mul_f32_e32 v158, v135, v154
	v_mul_f32_e32 v159, v223, v155
	v_mul_f32_e32 v177, v206, v156
	v_fmac_f32_e32 v177, v207, v157
	v_fmac_f32_e32 v177, v208, v158
	v_fmac_f32_e32 v177, v209, v159
	v_mul_f32_e32 v148, v148, v178
	v_mul_f32_e32 v149, v149, v178
	v_add_f32_dpp v177, v177, v177 quad_perm:[1,0,3,2] row_mask:0xf bank_mask:0xf bound_ctrl:1
	v_mul_f32_e32 v150, v150, v178
	v_mul_f32_e32 v151, v151, v178
	v_add_f32_dpp v177, v177, v177 quad_perm:[2,3,0,1] row_mask:0xf bank_mask:0xf bound_ctrl:1
	v_mul_f32_e32 v18, v18, v148
	v_mul_f32_e32 v19, v19, v149
	v_add_f32_dpp v177, v177, v177 row_half_mirror row_mask:0xf bank_mask:0xf bound_ctrl:1
	v_mul_f32_e32 v20, v20, v150
	v_mul_f32_e32 v21, v21, v151
	v_add_f32_dpp v177, v177, v177 row_mirror row_mask:0xf bank_mask:0xf bound_ctrl:1
	s_lshl_b32 s0, s56, 9
	s_add_u32 s62, s34, s0
	s_addc_u32 s63, s35, 0
	v_mul_f32_e32 v156, v138, v177
	v_mul_f32_e32 v157, v226, v177
	v_mul_f32_e32 v158, v139, v177
	v_mul_f32_e32 v159, v227, v177
	v_cvt_pk_bf16_f32 v72, v134, v222
	v_cvt_pk_bf16_f32 v73, v135, v223
	global_store_dwordx2 v250, v[72:73], s[62:63]
	v_cvt_pk_bf16_f32 v74, v14, v15
	v_cvt_pk_bf16_f32 v75, v16, v17
	s_add_u32 s0, s62, 0x500000
	s_addc_u32 s1, s63, 0
	global_store_dwordx2 v250, v[74:75], s[0:1]
	v_cvt_pk_bf16_f32 v180, v152, v153
	v_cvt_pk_bf16_f32 v181, v154, v155
	s_add_u32 s0, s62, 0xa00000
	s_addc_u32 s1, s63, 0
	global_store_dwordx2 v250, v[180:181], s[0:1]
	v_cvt_pk_bf16_f32 v72, v138, v226
	v_cvt_pk_bf16_f32 v73, v139, v227
	s_add_u32 s0, s62, 0xf00000
	s_addc_u32 s1, s63, 0
	global_store_dwordx2 v250, v[72:73], s[0:1]
	v_cvt_pk_bf16_f32 v74, v148, v149
	v_cvt_pk_bf16_f32 v75, v150, v151
	s_add_u32 s0, s62, 0x1400000
	s_addc_u32 s1, s63, 0
	global_store_dwordx2 v250, v[74:75], s[0:1]
	v_cvt_pk_bf16_f32 v180, v18, v19
	v_cvt_pk_bf16_f32 v181, v20, v21
	s_add_u32 s0, s62, 0x1900000
	s_addc_u32 s1, s63, 0
	global_store_dwordx2 v250, v[180:181], s[0:1]
	v_cvt_pk_bf16_f32 v72, v156, v157
	v_cvt_pk_bf16_f32 v73, v158, v159
	s_lshl_b32 s0, s56, 9
	s_add_u32 s0, s42, s0
	s_addc_u32 s1, s43, 0
	global_store_dwordx2 v250, v[72:73], s[0:1]
	s_add_i32 s56, s53, 12
	s_cmpk_lt_i32 s56, 0x2000
	s_movk_i32 s0, 0x3ff
	s_cselect_b32 s0, 0xff, s0
	s_and_b32 s1, s56, s0
	s_cmp_lg_u32 s1, 0
	s_cselect_b32 s59, 1.0, 0
	s_cselect_b32 s1, -1, 0
	s_add_i32 s1, s56, s1
	s_mul_i32 s0, s56, 0x1d00
	s_add_u32 s76, s28, s0
	s_addc_u32 s77, s29, 0
	s_mul_i32 s0, s1, 0x1d00
	s_add_u32 s78, s28, s0
	s_addc_u32 s79, s29, 0
	global_load_dwordx2 v[222:223], v250, s[76:77] offset:0
	global_load_dwordx2 v[224:225], v250, s[76:77] offset:512
	global_load_dwordx2 v[226:227], v250, s[76:77] offset:1024
	global_load_dwordx2 v[228:229], v250, s[78:79] offset:0
	global_load_dwordx2 v[230:231], v250, s[78:79] offset:512
	global_load_dwordx2 v[232:233], v250, s[78:79] offset:1024
	ds_read_b128 v[14:17], v31 offset:8192
	ds_read_b128 v[18:21], v31 offset:28672
	s_waitcnt vmcnt(19)
	v_lshlrev_b32_e32 v134, 16, v236
	v_and_b32_e32 v236, 0xffff0000, v236
	v_lshlrev_b32_e32 v135, 16, v237
	v_and_b32_e32 v237, 0xffff0000, v237
	v_lshlrev_b32_e32 v136, 16, v238
	v_and_b32_e32 v238, 0xffff0000, v238
	v_lshlrev_b32_e32 v137, 16, v239
	v_and_b32_e32 v239, 0xffff0000, v239
	v_lshlrev_b32_e32 v138, 16, v240
	v_and_b32_e32 v240, 0xffff0000, v240
	v_lshlrev_b32_e32 v139, 16, v241
	v_and_b32_e32 v241, 0xffff0000, v241
	v_lshlrev_b32_e32 v140, 16, v242
	v_and_b32_e32 v242, 0xffff0000, v242
	v_lshlrev_b32_e32 v141, 16, v243
	v_and_b32_e32 v243, 0xffff0000, v243
	v_lshlrev_b32_e32 v142, 16, v244
	v_and_b32_e32 v244, 0xffff0000, v244
	v_lshlrev_b32_e32 v143, 16, v245
	v_and_b32_e32 v245, 0xffff0000, v245
	v_lshlrev_b32_e32 v144, 16, v246
	v_and_b32_e32 v246, 0xffff0000, v246
	v_lshlrev_b32_e32 v145, 16, v247
	v_and_b32_e32 v247, 0xffff0000, v247
	v_fma_f32 v140, s60, v140, -v134
	v_fma_f32 v242, s60, v242, -v236
	v_fma_f32 v141, s60, v141, -v135
	v_fma_f32 v243, s60, v243, -v237
	v_fmac_f32_e32 v134, v210, v140
	v_fmac_f32_e32 v236, v211, v242
	v_fmac_f32_e32 v135, v212, v141
	v_fmac_f32_e32 v237, v213, v243
	v_fma_f32 v142, s60, v142, -v136
	v_fma_f32 v244, s60, v244, -v238
	v_fma_f32 v143, s60, v143, -v137
	v_fma_f32 v245, s60, v245, -v239
	v_fmac_f32_e32 v136, v214, v142
	v_fmac_f32_e32 v238, v215, v244
	v_fmac_f32_e32 v137, v216, v143
	v_fmac_f32_e32 v239, v217, v245
	v_fma_f32 v144, s60, v144, -v138
	v_fma_f32 v246, s60, v246, -v240
	v_fma_f32 v145, s60, v145, -v139
	v_fma_f32 v247, s60, v247, -v241
	v_fmac_f32_e32 v138, v218, v144
	v_fmac_f32_e32 v240, v219, v246
	v_fmac_f32_e32 v139, v220, v145
	v_fmac_f32_e32 v241, v221, v247
	v_mul_f32_e32 v148, v198, v136
	v_mul_f32_e32 v149, v199, v238
	v_mul_f32_e32 v150, v200, v137
	v_mul_f32_e32 v151, v201, v239
	v_mul_f32_e32 v176, v148, v148
	v_fmac_f32_e32 v176, v149, v149
	v_fmac_f32_e32 v176, v150, v150
	v_fmac_f32_e32 v176, v151, v151
	s_waitcnt lgkmcnt(2)
	v_fmamk_f32 v26, v26, 0xbfb8aa3b, v194
	v_fmamk_f32 v27, v27, 0xbfb8aa3b, v195
	v_fmamk_f32 v28, v28, 0xbfb8aa3b, v196
	v_fmamk_f32 v29, v29, 0xbfb8aa3b, v197
	v_add_f32_dpp v176, v176, v176 quad_perm:[1,0,3,2] row_mask:0xf bank_mask:0xf bound_ctrl:1
	v_exp_f32_e32 v26, v26
	v_exp_f32_e32 v27, v27
	v_exp_f32_e32 v28, v28
	v_exp_f32_e32 v29, v29
	v_add_f32_dpp v176, v176, v176 quad_perm:[2,3,0,1] row_mask:0xf bank_mask:0xf bound_ctrl:1
	v_add_f32_e32 v26, 1.0, v26
	v_add_f32_e32 v27, 1.0, v27
	v_add_f32_e32 v28, 1.0, v28
	v_add_f32_e32 v29, 1.0, v29
	v_add_f32_dpp v176, v176, v176 row_half_mirror row_mask:0xf bank_mask:0xf bound_ctrl:1
	v_rcp_f32_e32 v26, v26
	v_rcp_f32_e32 v27, v27
	v_rcp_f32_e32 v28, v28
	v_rcp_f32_e32 v29, v29
	v_add_f32_dpp v176, v176, v176 row_mirror row_mask:0xf bank_mask:0xf bound_ctrl:1
	v_fmamk_f32 v22, v22, 0xbfb8aa3b, v190
	v_fmamk_f32 v23, v23, 0xbfb8aa3b, v191
	v_fmamk_f32 v24, v24, 0xbfb8aa3b, v192
	v_fmamk_f32 v25, v25, 0xbfb8aa3b, v193
	v_sqrt_f32_e32 v176, v176
	v_exp_f32_e32 v22, v22
	v_exp_f32_e32 v23, v23
	v_exp_f32_e32 v24, v24
	v_exp_f32_e32 v25, v25
	v_max_f32_e32 v176, 0x2b8cbccc, v176
	v_add_f32_e32 v22, 1.0, v22
	v_add_f32_e32 v23, 1.0, v23
	v_add_f32_e32 v24, 1.0, v24
	v_add_f32_e32 v25, 1.0, v25
	v_rcp_f32_e32 v178, v176
	v_rcp_f32_e32 v22, v22
	v_rcp_f32_e32 v23, v23
	v_rcp_f32_e32 v24, v24
	v_rcp_f32_e32 v25, v25
	v_mul_f32_e32 v22, 0xbf60028a, v22
	v_mul_f32_e32 v23, 0xbf60028a, v23
	v_mul_f32_e32 v24, 0xbf60028a, v24
	v_mul_f32_e32 v25, 0xbf60028a, v25
	v_exp_f32_e32 v22, v22
	v_exp_f32_e32 v23, v23
	v_exp_f32_e32 v24, v24
	v_exp_f32_e32 v25, v25
	v_add_f32_e32 v152, -1.0, v26
	v_add_f32_e32 v153, -1.0, v27
	v_add_f32_e32 v154, -1.0, v28
	v_add_f32_e32 v155, -1.0, v29
	v_fma_f32 v152, v202, v152, 1.0
	v_fma_f32 v153, v203, v153, 1.0
	v_fma_f32 v154, v204, v154, 1.0
	v_fma_f32 v155, v205, v155, 1.0
	v_mul_f32_e32 v152, v136, v152
	v_mul_f32_e32 v153, v238, v153
	v_mul_f32_e32 v154, v137, v154
	v_mul_f32_e32 v155, v239, v155
	v_mul_f32_e32 v156, v134, v152
	v_mul_f32_e32 v157, v236, v153
	v_mul_f32_e32 v158, v135, v154
	v_mul_f32_e32 v159, v237, v155
	v_mul_f32_e32 v177, v206, v156
	v_fmac_f32_e32 v177, v207, v157
	v_fmac_f32_e32 v177, v208, v158
	v_fmac_f32_e32 v177, v209, v159
	v_mul_f32_e32 v148, v148, v178
	v_mul_f32_e32 v149, v149, v178
	v_add_f32_dpp v177, v177, v177 quad_perm:[1,0,3,2] row_mask:0xf bank_mask:0xf bound_ctrl:1
	v_mul_f32_e32 v150, v150, v178
	v_mul_f32_e32 v151, v151, v178
	v_add_f32_dpp v177, v177, v177 quad_perm:[2,3,0,1] row_mask:0xf bank_mask:0xf bound_ctrl:1
	v_mul_f32_e32 v26, v26, v148
	v_mul_f32_e32 v27, v27, v149
	v_add_f32_dpp v177, v177, v177 row_half_mirror row_mask:0xf bank_mask:0xf bound_ctrl:1
	v_mul_f32_e32 v28, v28, v150
	v_mul_f32_e32 v29, v29, v151
	v_add_f32_dpp v177, v177, v177 row_mirror row_mask:0xf bank_mask:0xf bound_ctrl:1
	s_lshl_b32 s0, s57, 9
	s_add_u32 s62, s34, s0
	s_addc_u32 s63, s35, 0
	v_mul_f32_e32 v156, v138, v177
	v_mul_f32_e32 v157, v240, v177
	v_mul_f32_e32 v158, v139, v177
	v_mul_f32_e32 v159, v241, v177
	v_cvt_pk_bf16_f32 v72, v134, v236
	v_cvt_pk_bf16_f32 v73, v135, v237
	global_store_dwordx2 v250, v[72:73], s[62:63]
	v_cvt_pk_bf16_f32 v74, v22, v23
	v_cvt_pk_bf16_f32 v75, v24, v25
	s_add_u32 s0, s62, 0x500000
	s_addc_u32 s1, s63, 0
	global_store_dwordx2 v250, v[74:75], s[0:1]
	v_cvt_pk_bf16_f32 v180, v152, v153
	v_cvt_pk_bf16_f32 v181, v154, v155
	s_add_u32 s0, s62, 0xa00000
	s_addc_u32 s1, s63, 0
	global_store_dwordx2 v250, v[180:181], s[0:1]
	v_cvt_pk_bf16_f32 v72, v138, v240
	v_cvt_pk_bf16_f32 v73, v139, v241
	s_add_u32 s0, s62, 0xf00000
	s_addc_u32 s1, s63, 0
	global_store_dwordx2 v250, v[72:73], s[0:1]
	v_cvt_pk_bf16_f32 v74, v148, v149
	v_cvt_pk_bf16_f32 v75, v150, v151
	s_add_u32 s0, s62, 0x1400000
	s_addc_u32 s1, s63, 0
	global_store_dwordx2 v250, v[74:75], s[0:1]
	v_cvt_pk_bf16_f32 v180, v26, v27
	v_cvt_pk_bf16_f32 v181, v28, v29
	s_add_u32 s0, s62, 0x1900000
	s_addc_u32 s1, s63, 0
	global_store_dwordx2 v250, v[180:181], s[0:1]
	v_cvt_pk_bf16_f32 v72, v156, v157
	v_cvt_pk_bf16_f32 v73, v158, v159
	s_lshl_b32 s0, s57, 9
	s_add_u32 s0, s42, s0
	s_addc_u32 s1, s43, 0
	global_store_dwordx2 v250, v[72:73], s[0:1]
	s_add_i32 s57, s53, 16
	s_cmpk_lt_i32 s57, 0x2000
	s_movk_i32 s0, 0x3ff
	s_cselect_b32 s0, 0xff, s0
	s_and_b32 s1, s57, s0
	s_cmp_lg_u32 s1, 0
	s_cselect_b32 s60, 1.0, 0
	s_cselect_b32 s1, -1, 0
	s_add_i32 s1, s57, s1
	s_mul_i32 s0, s57, 0x1d00
	s_add_u32 s80, s28, s0
	s_addc_u32 s81, s29, 0
	s_mul_i32 s0, s1, 0x1d00
	s_add_u32 s82, s28, s0
	s_addc_u32 s83, s29, 0
	global_load_dwordx2 v[236:237], v250, s[80:81] offset:0
	global_load_dwordx2 v[238:239], v250, s[80:81] offset:512
	global_load_dwordx2 v[240:241], v250, s[80:81] offset:1024
	global_load_dwordx2 v[242:243], v250, s[82:83] offset:0
	global_load_dwordx2 v[244:245], v250, s[82:83] offset:512
	global_load_dwordx2 v[246:247], v250, s[82:83] offset:1024
	ds_read_b128 v[22:25], v31 offset:12288
	ds_read_b128 v[26:29], v31 offset:32768
	s_waitcnt vmcnt(26)
	v_lshlrev_b32_e32 v134, 16, v0
	v_and_b32_e32 v0, 0xffff0000, v0
	v_lshlrev_b32_e32 v135, 16, v1
	v_and_b32_e32 v1, 0xffff0000, v1
	v_lshlrev_b32_e32 v136, 16, v2
	v_and_b32_e32 v2, 0xffff0000, v2
	v_lshlrev_b32_e32 v137, 16, v3
	v_and_b32_e32 v3, 0xffff0000, v3
	v_lshlrev_b32_e32 v138, 16, v4
	v_and_b32_e32 v4, 0xffff0000, v4
	v_lshlrev_b32_e32 v139, 16, v5
	v_and_b32_e32 v5, 0xffff0000, v5
	v_lshlrev_b32_e32 v140, 16, v6
	v_and_b32_e32 v6, 0xffff0000, v6
	v_lshlrev_b32_e32 v141, 16, v7
	v_and_b32_e32 v7, 0xffff0000, v7
	v_lshlrev_b32_e32 v142, 16, v8
	v_and_b32_e32 v8, 0xffff0000, v8
	v_lshlrev_b32_e32 v143, 16, v9
	v_and_b32_e32 v9, 0xffff0000, v9
	v_lshlrev_b32_e32 v144, 16, v10
	v_and_b32_e32 v10, 0xffff0000, v10
	v_lshlrev_b32_e32 v145, 16, v11
	v_and_b32_e32 v11, 0xffff0000, v11
	v_fma_f32 v140, s61, v140, -v134
	v_fma_f32 v6, s61, v6, -v0
	v_fma_f32 v141, s61, v141, -v135
	v_fma_f32 v7, s61, v7, -v1
	v_fmac_f32_e32 v134, v210, v140
	v_fmac_f32_e32 v0, v211, v6
	v_fmac_f32_e32 v135, v212, v141
	v_fmac_f32_e32 v1, v213, v7
	v_fma_f32 v142, s61, v142, -v136
	v_fma_f32 v8, s61, v8, -v2
	v_fma_f32 v143, s61, v143, -v137
	v_fma_f32 v9, s61, v9, -v3
	v_fmac_f32_e32 v136, v214, v142
	v_fmac_f32_e32 v2, v215, v8
	v_fmac_f32_e32 v137, v216, v143
	v_fmac_f32_e32 v3, v217, v9
	v_fma_f32 v144, s61, v144, -v138
	v_fma_f32 v10, s61, v10, -v4
	v_fma_f32 v145, s61, v145, -v139
	v_fma_f32 v11, s61, v11, -v5
	v_fmac_f32_e32 v138, v218, v144
	v_fmac_f32_e32 v4, v219, v10
	v_fmac_f32_e32 v139, v220, v145
	v_fmac_f32_e32 v5, v221, v11
	v_mul_f32_e32 v148, v198, v136
	v_mul_f32_e32 v149, v199, v2
	v_mul_f32_e32 v150, v200, v137
	v_mul_f32_e32 v151, v201, v3
	v_mul_f32_e32 v176, v148, v148
	v_fmac_f32_e32 v176, v149, v149
	v_fmac_f32_e32 v176, v150, v150
	v_fmac_f32_e32 v176, v151, v151
	s_waitcnt lgkmcnt(2)
	v_fmamk_f32 v18, v18, 0xbfb8aa3b, v194
	v_fmamk_f32 v19, v19, 0xbfb8aa3b, v195
	v_fmamk_f32 v20, v20, 0xbfb8aa3b, v196
	v_fmamk_f32 v21, v21, 0xbfb8aa3b, v197
	v_add_f32_dpp v176, v176, v176 quad_perm:[1,0,3,2] row_mask:0xf bank_mask:0xf bound_ctrl:1
	v_exp_f32_e32 v18, v18
	v_exp_f32_e32 v19, v19
	v_exp_f32_e32 v20, v20
	v_exp_f32_e32 v21, v21
	v_add_f32_dpp v176, v176, v176 quad_perm:[2,3,0,1] row_mask:0xf bank_mask:0xf bound_ctrl:1
	v_add_f32_e32 v18, 1.0, v18
	v_add_f32_e32 v19, 1.0, v19
	v_add_f32_e32 v20, 1.0, v20
	v_add_f32_e32 v21, 1.0, v21
	v_add_f32_dpp v176, v176, v176 row_half_mirror row_mask:0xf bank_mask:0xf bound_ctrl:1
	v_rcp_f32_e32 v18, v18
	v_rcp_f32_e32 v19, v19
	v_rcp_f32_e32 v20, v20
	v_rcp_f32_e32 v21, v21
	v_add_f32_dpp v176, v176, v176 row_mirror row_mask:0xf bank_mask:0xf bound_ctrl:1
	v_fmamk_f32 v14, v14, 0xbfb8aa3b, v190
	v_fmamk_f32 v15, v15, 0xbfb8aa3b, v191
	v_fmamk_f32 v16, v16, 0xbfb8aa3b, v192
	v_fmamk_f32 v17, v17, 0xbfb8aa3b, v193
	v_sqrt_f32_e32 v176, v176
	v_exp_f32_e32 v14, v14
	v_exp_f32_e32 v15, v15
	v_exp_f32_e32 v16, v16
	v_exp_f32_e32 v17, v17
	v_max_f32_e32 v176, 0x2b8cbccc, v176
	v_add_f32_e32 v14, 1.0, v14
	v_add_f32_e32 v15, 1.0, v15
	v_add_f32_e32 v16, 1.0, v16
	v_add_f32_e32 v17, 1.0, v17
	v_rcp_f32_e32 v178, v176
	v_rcp_f32_e32 v14, v14
	v_rcp_f32_e32 v15, v15
	v_rcp_f32_e32 v16, v16
	v_rcp_f32_e32 v17, v17
	v_mul_f32_e32 v14, 0xbf60028a, v14
	v_mul_f32_e32 v15, 0xbf60028a, v15
	v_mul_f32_e32 v16, 0xbf60028a, v16
	v_mul_f32_e32 v17, 0xbf60028a, v17
	v_exp_f32_e32 v14, v14
	v_exp_f32_e32 v15, v15
	v_exp_f32_e32 v16, v16
	v_exp_f32_e32 v17, v17
	v_add_f32_e32 v152, -1.0, v18
	v_add_f32_e32 v153, -1.0, v19
	v_add_f32_e32 v154, -1.0, v20
	v_add_f32_e32 v155, -1.0, v21
	v_fma_f32 v152, v202, v152, 1.0
	v_fma_f32 v153, v203, v153, 1.0
	v_fma_f32 v154, v204, v154, 1.0
	v_fma_f32 v155, v205, v155, 1.0
	v_mul_f32_e32 v152, v136, v152
	v_mul_f32_e32 v153, v2, v153
	v_mul_f32_e32 v154, v137, v154
	v_mul_f32_e32 v155, v3, v155
	v_mul_f32_e32 v156, v134, v152
	v_mul_f32_e32 v157, v0, v153
	v_mul_f32_e32 v158, v135, v154
	v_mul_f32_e32 v159, v1, v155
	v_mul_f32_e32 v177, v206, v156
	v_fmac_f32_e32 v177, v207, v157
	v_fmac_f32_e32 v177, v208, v158
	v_fmac_f32_e32 v177, v209, v159
	v_mul_f32_e32 v148, v148, v178
	v_mul_f32_e32 v149, v149, v178
	v_add_f32_dpp v177, v177, v177 quad_perm:[1,0,3,2] row_mask:0xf bank_mask:0xf bound_ctrl:1
	v_mul_f32_e32 v150, v150, v178
	v_mul_f32_e32 v151, v151, v178
	v_add_f32_dpp v177, v177, v177 quad_perm:[2,3,0,1] row_mask:0xf bank_mask:0xf bound_ctrl:1
	v_mul_f32_e32 v18, v18, v148
	v_mul_f32_e32 v19, v19, v149
	v_add_f32_dpp v177, v177, v177 row_half_mirror row_mask:0xf bank_mask:0xf bound_ctrl:1
	v_mul_f32_e32 v20, v20, v150
	v_mul_f32_e32 v21, v21, v151
	v_add_f32_dpp v177, v177, v177 row_mirror row_mask:0xf bank_mask:0xf bound_ctrl:1
	s_lshl_b32 s0, s58, 9
	s_add_u32 s62, s34, s0
	s_addc_u32 s63, s35, 0
	v_mul_f32_e32 v156, v138, v177
	v_mul_f32_e32 v157, v4, v177
	v_mul_f32_e32 v158, v139, v177
	v_mul_f32_e32 v159, v5, v177
	v_cvt_pk_bf16_f32 v72, v134, v0
	v_cvt_pk_bf16_f32 v73, v135, v1
	global_store_dwordx2 v250, v[72:73], s[62:63]
	v_cvt_pk_bf16_f32 v74, v14, v15
	v_cvt_pk_bf16_f32 v75, v16, v17
	s_add_u32 s0, s62, 0x500000
	s_addc_u32 s1, s63, 0
	global_store_dwordx2 v250, v[74:75], s[0:1]
	v_cvt_pk_bf16_f32 v180, v152, v153
	v_cvt_pk_bf16_f32 v181, v154, v155
	s_add_u32 s0, s62, 0xa00000
	s_addc_u32 s1, s63, 0
	global_store_dwordx2 v250, v[180:181], s[0:1]
	v_cvt_pk_bf16_f32 v72, v138, v4
	v_cvt_pk_bf16_f32 v73, v139, v5
	s_add_u32 s0, s62, 0xf00000
	s_addc_u32 s1, s63, 0
	global_store_dwordx2 v250, v[72:73], s[0:1]
	v_cvt_pk_bf16_f32 v74, v148, v149
	v_cvt_pk_bf16_f32 v75, v150, v151
	s_add_u32 s0, s62, 0x1400000
	s_addc_u32 s1, s63, 0
	global_store_dwordx2 v250, v[74:75], s[0:1]
	v_cvt_pk_bf16_f32 v180, v18, v19
	v_cvt_pk_bf16_f32 v181, v20, v21
	s_add_u32 s0, s62, 0x1900000
	s_addc_u32 s1, s63, 0
	global_store_dwordx2 v250, v[180:181], s[0:1]
	v_cvt_pk_bf16_f32 v72, v156, v157
	v_cvt_pk_bf16_f32 v73, v158, v159
	s_lshl_b32 s0, s58, 9
	s_add_u32 s0, s42, s0
	s_addc_u32 s1, s43, 0
	global_store_dwordx2 v250, v[72:73], s[0:1]
	ds_read_b128 v[14:17], v31 offset:16384
	ds_read_b128 v[18:21], v31 offset:36864
	s_waitcnt vmcnt(20)
	v_lshlrev_b32_e32 v134, 16, v222
	v_and_b32_e32 v222, 0xffff0000, v222
	v_lshlrev_b32_e32 v135, 16, v223
	v_and_b32_e32 v223, 0xffff0000, v223
	v_lshlrev_b32_e32 v136, 16, v224
	v_and_b32_e32 v224, 0xffff0000, v224
	v_lshlrev_b32_e32 v137, 16, v225
	v_and_b32_e32 v225, 0xffff0000, v225
	v_lshlrev_b32_e32 v138, 16, v226
	v_and_b32_e32 v226, 0xffff0000, v226
	v_lshlrev_b32_e32 v139, 16, v227
	v_and_b32_e32 v227, 0xffff0000, v227
	v_lshlrev_b32_e32 v140, 16, v228
	v_and_b32_e32 v228, 0xffff0000, v228
	v_lshlrev_b32_e32 v141, 16, v229
	v_and_b32_e32 v229, 0xffff0000, v229
	v_lshlrev_b32_e32 v142, 16, v230
	v_and_b32_e32 v230, 0xffff0000, v230
	v_lshlrev_b32_e32 v143, 16, v231
	v_and_b32_e32 v231, 0xffff0000, v231
	v_lshlrev_b32_e32 v144, 16, v232
	v_and_b32_e32 v232, 0xffff0000, v232
	v_lshlrev_b32_e32 v145, 16, v233
	v_and_b32_e32 v233, 0xffff0000, v233
	v_fma_f32 v140, s59, v140, -v134
	v_fma_f32 v228, s59, v228, -v222
	v_fma_f32 v141, s59, v141, -v135
	v_fma_f32 v229, s59, v229, -v223
	v_fmac_f32_e32 v134, v210, v140
	v_fmac_f32_e32 v222, v211, v228
	v_fmac_f32_e32 v135, v212, v141
	v_fmac_f32_e32 v223, v213, v229
	v_fma_f32 v142, s59, v142, -v136
	v_fma_f32 v230, s59, v230, -v224
	v_fma_f32 v143, s59, v143, -v137
	v_fma_f32 v231, s59, v231, -v225
	v_fmac_f32_e32 v136, v214, v142
	v_fmac_f32_e32 v224, v215, v230
	v_fmac_f32_e32 v137, v216, v143
	v_fmac_f32_e32 v225, v217, v231
	v_fma_f32 v144, s59, v144, -v138
	v_fma_f32 v232, s59, v232, -v226
	v_fma_f32 v145, s59, v145, -v139
	v_fma_f32 v233, s59, v233, -v227
	v_fmac_f32_e32 v138, v218, v144
	v_fmac_f32_e32 v226, v219, v232
	v_fmac_f32_e32 v139, v220, v145
	v_fmac_f32_e32 v227, v221, v233
	v_mul_f32_e32 v148, v198, v136
	v_mul_f32_e32 v149, v199, v224
	v_mul_f32_e32 v150, v200, v137
	v_mul_f32_e32 v151, v201, v225
	v_mul_f32_e32 v176, v148, v148
	v_fmac_f32_e32 v176, v149, v149
	v_fmac_f32_e32 v176, v150, v150
	v_fmac_f32_e32 v176, v151, v151
	s_waitcnt lgkmcnt(2)
	v_fmamk_f32 v26, v26, 0xbfb8aa3b, v194
	v_fmamk_f32 v27, v27, 0xbfb8aa3b, v195
	v_fmamk_f32 v28, v28, 0xbfb8aa3b, v196
	v_fmamk_f32 v29, v29, 0xbfb8aa3b, v197
	v_add_f32_dpp v176, v176, v176 quad_perm:[1,0,3,2] row_mask:0xf bank_mask:0xf bound_ctrl:1
	v_exp_f32_e32 v26, v26
	v_exp_f32_e32 v27, v27
	v_exp_f32_e32 v28, v28
	v_exp_f32_e32 v29, v29
	v_add_f32_dpp v176, v176, v176 quad_perm:[2,3,0,1] row_mask:0xf bank_mask:0xf bound_ctrl:1
	v_add_f32_e32 v26, 1.0, v26
	v_add_f32_e32 v27, 1.0, v27
	v_add_f32_e32 v28, 1.0, v28
	v_add_f32_e32 v29, 1.0, v29
	v_add_f32_dpp v176, v176, v176 row_half_mirror row_mask:0xf bank_mask:0xf bound_ctrl:1
	v_rcp_f32_e32 v26, v26
	v_rcp_f32_e32 v27, v27
	v_rcp_f32_e32 v28, v28
	v_rcp_f32_e32 v29, v29
	v_add_f32_dpp v176, v176, v176 row_mirror row_mask:0xf bank_mask:0xf bound_ctrl:1
	v_fmamk_f32 v22, v22, 0xbfb8aa3b, v190
	v_fmamk_f32 v23, v23, 0xbfb8aa3b, v191
	v_fmamk_f32 v24, v24, 0xbfb8aa3b, v192
	v_fmamk_f32 v25, v25, 0xbfb8aa3b, v193
	v_sqrt_f32_e32 v176, v176
	v_exp_f32_e32 v22, v22
	v_exp_f32_e32 v23, v23
	v_exp_f32_e32 v24, v24
	v_exp_f32_e32 v25, v25
	v_max_f32_e32 v176, 0x2b8cbccc, v176
	v_add_f32_e32 v22, 1.0, v22
	v_add_f32_e32 v23, 1.0, v23
	v_add_f32_e32 v24, 1.0, v24
	v_add_f32_e32 v25, 1.0, v25
	v_rcp_f32_e32 v178, v176
	v_rcp_f32_e32 v22, v22
	v_rcp_f32_e32 v23, v23
	v_rcp_f32_e32 v24, v24
	v_rcp_f32_e32 v25, v25
	v_mul_f32_e32 v22, 0xbf60028a, v22
	v_mul_f32_e32 v23, 0xbf60028a, v23
	v_mul_f32_e32 v24, 0xbf60028a, v24
	v_mul_f32_e32 v25, 0xbf60028a, v25
	v_exp_f32_e32 v22, v22
	v_exp_f32_e32 v23, v23
	v_exp_f32_e32 v24, v24
	v_exp_f32_e32 v25, v25
	v_add_f32_e32 v152, -1.0, v26
	v_add_f32_e32 v153, -1.0, v27
	v_add_f32_e32 v154, -1.0, v28
	v_add_f32_e32 v155, -1.0, v29
	v_fma_f32 v152, v202, v152, 1.0
	v_fma_f32 v153, v203, v153, 1.0
	v_fma_f32 v154, v204, v154, 1.0
	v_fma_f32 v155, v205, v155, 1.0
	v_mul_f32_e32 v152, v136, v152
	v_mul_f32_e32 v153, v224, v153
	v_mul_f32_e32 v154, v137, v154
	v_mul_f32_e32 v155, v225, v155
	v_mul_f32_e32 v156, v134, v152
	v_mul_f32_e32 v157, v222, v153
	v_mul_f32_e32 v158, v135, v154
	v_mul_f32_e32 v159, v223, v155
	v_mul_f32_e32 v177, v206, v156
	v_fmac_f32_e32 v177, v207, v157
	v_fmac_f32_e32 v177, v208, v158
	v_fmac_f32_e32 v177, v209, v159
	v_mul_f32_e32 v148, v148, v178
	v_mul_f32_e32 v149, v149, v178
	v_add_f32_dpp v177, v177, v177 quad_perm:[1,0,3,2] row_mask:0xf bank_mask:0xf bound_ctrl:1
	v_mul_f32_e32 v150, v150, v178
	v_mul_f32_e32 v151, v151, v178
	v_add_f32_dpp v177, v177, v177 quad_perm:[2,3,0,1] row_mask:0xf bank_mask:0xf bound_ctrl:1
	v_mul_f32_e32 v26, v26, v148
	v_mul_f32_e32 v27, v27, v149
	v_add_f32_dpp v177, v177, v177 row_half_mirror row_mask:0xf bank_mask:0xf bound_ctrl:1
	v_mul_f32_e32 v28, v28, v150
	v_mul_f32_e32 v29, v29, v151
	v_add_f32_dpp v177, v177, v177 row_mirror row_mask:0xf bank_mask:0xf bound_ctrl:1
	s_lshl_b32 s0, s56, 9
	s_add_u32 s62, s34, s0
	s_addc_u32 s63, s35, 0
	v_mul_f32_e32 v156, v138, v177
	v_mul_f32_e32 v157, v226, v177
	v_mul_f32_e32 v158, v139, v177
	v_mul_f32_e32 v159, v227, v177
	v_cvt_pk_bf16_f32 v72, v134, v222
	v_cvt_pk_bf16_f32 v73, v135, v223
	global_store_dwordx2 v250, v[72:73], s[62:63]
	v_cvt_pk_bf16_f32 v74, v22, v23
	v_cvt_pk_bf16_f32 v75, v24, v25
	s_add_u32 s0, s62, 0x500000
	s_addc_u32 s1, s63, 0
	global_store_dwordx2 v250, v[74:75], s[0:1]
	v_cvt_pk_bf16_f32 v180, v152, v153
	v_cvt_pk_bf16_f32 v181, v154, v155
	s_add_u32 s0, s62, 0xa00000
	s_addc_u32 s1, s63, 0
	global_store_dwordx2 v250, v[180:181], s[0:1]
	v_cvt_pk_bf16_f32 v72, v138, v226
	v_cvt_pk_bf16_f32 v73, v139, v227
	s_add_u32 s0, s62, 0xf00000
	s_addc_u32 s1, s63, 0
	global_store_dwordx2 v250, v[72:73], s[0:1]
	v_cvt_pk_bf16_f32 v74, v148, v149
	v_cvt_pk_bf16_f32 v75, v150, v151
	s_add_u32 s0, s62, 0x1400000
	s_addc_u32 s1, s63, 0
	global_store_dwordx2 v250, v[74:75], s[0:1]
	v_cvt_pk_bf16_f32 v180, v26, v27
	v_cvt_pk_bf16_f32 v181, v28, v29
	s_add_u32 s0, s62, 0x1900000
	s_addc_u32 s1, s63, 0
	global_store_dwordx2 v250, v[180:181], s[0:1]
	v_cvt_pk_bf16_f32 v72, v156, v157
	v_cvt_pk_bf16_f32 v73, v158, v159
	s_lshl_b32 s0, s56, 9
	s_add_u32 s0, s42, s0
	s_addc_u32 s1, s43, 0
	global_store_dwordx2 v250, v[72:73], s[0:1]
	s_waitcnt vmcnt(14)
	v_lshlrev_b32_e32 v134, 16, v236
	v_and_b32_e32 v236, 0xffff0000, v236
	v_lshlrev_b32_e32 v135, 16, v237
	v_and_b32_e32 v237, 0xffff0000, v237
	v_lshlrev_b32_e32 v136, 16, v238
	v_and_b32_e32 v238, 0xffff0000, v238
	v_lshlrev_b32_e32 v137, 16, v239
	v_and_b32_e32 v239, 0xffff0000, v239
	v_lshlrev_b32_e32 v138, 16, v240
	v_and_b32_e32 v240, 0xffff0000, v240
	v_lshlrev_b32_e32 v139, 16, v241
	v_and_b32_e32 v241, 0xffff0000, v241
	v_lshlrev_b32_e32 v140, 16, v242
	v_and_b32_e32 v242, 0xffff0000, v242
	v_lshlrev_b32_e32 v141, 16, v243
	v_and_b32_e32 v243, 0xffff0000, v243
	v_lshlrev_b32_e32 v142, 16, v244
	v_and_b32_e32 v244, 0xffff0000, v244
	v_lshlrev_b32_e32 v143, 16, v245
	v_and_b32_e32 v245, 0xffff0000, v245
	v_lshlrev_b32_e32 v144, 16, v246
	v_and_b32_e32 v246, 0xffff0000, v246
	v_lshlrev_b32_e32 v145, 16, v247
	v_and_b32_e32 v247, 0xffff0000, v247
	v_fma_f32 v140, s60, v140, -v134
	v_fma_f32 v242, s60, v242, -v236
	v_fma_f32 v141, s60, v141, -v135
	v_fma_f32 v243, s60, v243, -v237
	v_fmac_f32_e32 v134, v210, v140
	v_fmac_f32_e32 v236, v211, v242
	v_fmac_f32_e32 v135, v212, v141
	v_fmac_f32_e32 v237, v213, v243
	v_fma_f32 v142, s60, v142, -v136
	v_fma_f32 v244, s60, v244, -v238
	v_fma_f32 v143, s60, v143, -v137
	v_fma_f32 v245, s60, v245, -v239
	v_fmac_f32_e32 v136, v214, v142
	v_fmac_f32_e32 v238, v215, v244
	v_fmac_f32_e32 v137, v216, v143
	v_fmac_f32_e32 v239, v217, v245
	v_fma_f32 v144, s60, v144, -v138
	v_fma_f32 v246, s60, v246, -v240
	v_fma_f32 v145, s60, v145, -v139
	v_fma_f32 v247, s60, v247, -v241
	v_fmac_f32_e32 v138, v218, v144
	v_fmac_f32_e32 v240, v219, v246
	v_fmac_f32_e32 v139, v220, v145
	v_fmac_f32_e32 v241, v221, v247
	v_mul_f32_e32 v148, v198, v136
	v_mul_f32_e32 v149, v199, v238
	v_mul_f32_e32 v150, v200, v137
	v_mul_f32_e32 v151, v201, v239
	v_mul_f32_e32 v176, v148, v148
	v_fmac_f32_e32 v176, v149, v149
	v_fmac_f32_e32 v176, v150, v150
	v_fmac_f32_e32 v176, v151, v151
	s_waitcnt lgkmcnt(0)
	v_fmamk_f32 v18, v18, 0xbfb8aa3b, v194
	v_fmamk_f32 v19, v19, 0xbfb8aa3b, v195
	v_fmamk_f32 v20, v20, 0xbfb8aa3b, v196
	v_fmamk_f32 v21, v21, 0xbfb8aa3b, v197
	v_add_f32_dpp v176, v176, v176 quad_perm:[1,0,3,2] row_mask:0xf bank_mask:0xf bound_ctrl:1
	v_exp_f32_e32 v18, v18
	v_exp_f32_e32 v19, v19
	v_exp_f32_e32 v20, v20
	v_exp_f32_e32 v21, v21
	v_add_f32_dpp v176, v176, v176 quad_perm:[2,3,0,1] row_mask:0xf bank_mask:0xf bound_ctrl:1
	v_add_f32_e32 v18, 1.0, v18
	v_add_f32_e32 v19, 1.0, v19
	v_add_f32_e32 v20, 1.0, v20
	v_add_f32_e32 v21, 1.0, v21
	v_add_f32_dpp v176, v176, v176 row_half_mirror row_mask:0xf bank_mask:0xf bound_ctrl:1
	v_rcp_f32_e32 v18, v18
	v_rcp_f32_e32 v19, v19
	v_rcp_f32_e32 v20, v20
	v_rcp_f32_e32 v21, v21
	v_add_f32_dpp v176, v176, v176 row_mirror row_mask:0xf bank_mask:0xf bound_ctrl:1
	v_fmamk_f32 v14, v14, 0xbfb8aa3b, v190
	v_fmamk_f32 v15, v15, 0xbfb8aa3b, v191
	v_fmamk_f32 v16, v16, 0xbfb8aa3b, v192
	v_fmamk_f32 v17, v17, 0xbfb8aa3b, v193
	v_sqrt_f32_e32 v176, v176
	v_exp_f32_e32 v14, v14
	v_exp_f32_e32 v15, v15
	v_exp_f32_e32 v16, v16
	v_exp_f32_e32 v17, v17
	v_max_f32_e32 v176, 0x2b8cbccc, v176
	v_add_f32_e32 v14, 1.0, v14
	v_add_f32_e32 v15, 1.0, v15
	v_add_f32_e32 v16, 1.0, v16
	v_add_f32_e32 v17, 1.0, v17
	v_rcp_f32_e32 v178, v176
	v_rcp_f32_e32 v14, v14
	v_rcp_f32_e32 v15, v15
	v_rcp_f32_e32 v16, v16
	v_rcp_f32_e32 v17, v17
	v_mul_f32_e32 v14, 0xbf60028a, v14
	v_mul_f32_e32 v15, 0xbf60028a, v15
	v_mul_f32_e32 v16, 0xbf60028a, v16
	v_mul_f32_e32 v17, 0xbf60028a, v17
	v_exp_f32_e32 v14, v14
	v_exp_f32_e32 v15, v15
	v_exp_f32_e32 v16, v16
	v_exp_f32_e32 v17, v17
	v_add_f32_e32 v152, -1.0, v18
	v_add_f32_e32 v153, -1.0, v19
	v_add_f32_e32 v154, -1.0, v20
	v_add_f32_e32 v155, -1.0, v21
	v_fma_f32 v152, v202, v152, 1.0
	v_fma_f32 v153, v203, v153, 1.0
	v_fma_f32 v154, v204, v154, 1.0
	v_fma_f32 v155, v205, v155, 1.0
	v_mul_f32_e32 v152, v136, v152
	v_mul_f32_e32 v153, v238, v153
	v_mul_f32_e32 v154, v137, v154
	v_mul_f32_e32 v155, v239, v155
	v_mul_f32_e32 v156, v134, v152
	v_mul_f32_e32 v157, v236, v153
	v_mul_f32_e32 v158, v135, v154
	v_mul_f32_e32 v159, v237, v155
	v_mul_f32_e32 v177, v206, v156
	v_fmac_f32_e32 v177, v207, v157
	v_fmac_f32_e32 v177, v208, v158
	v_fmac_f32_e32 v177, v209, v159
	v_mul_f32_e32 v148, v148, v178
	v_mul_f32_e32 v149, v149, v178
	v_add_f32_dpp v177, v177, v177 quad_perm:[1,0,3,2] row_mask:0xf bank_mask:0xf bound_ctrl:1
	v_mul_f32_e32 v150, v150, v178
	v_mul_f32_e32 v151, v151, v178
	v_add_f32_dpp v177, v177, v177 quad_perm:[2,3,0,1] row_mask:0xf bank_mask:0xf bound_ctrl:1
	v_mul_f32_e32 v18, v18, v148
	v_mul_f32_e32 v19, v19, v149
	v_add_f32_dpp v177, v177, v177 row_half_mirror row_mask:0xf bank_mask:0xf bound_ctrl:1
	v_mul_f32_e32 v20, v20, v150
	v_mul_f32_e32 v21, v21, v151
	v_add_f32_dpp v177, v177, v177 row_mirror row_mask:0xf bank_mask:0xf bound_ctrl:1
	s_lshl_b32 s0, s57, 9
	s_add_u32 s62, s34, s0
	s_addc_u32 s63, s35, 0
	v_mul_f32_e32 v156, v138, v177
	v_mul_f32_e32 v157, v240, v177
	v_mul_f32_e32 v158, v139, v177
	v_mul_f32_e32 v159, v241, v177
	v_cvt_pk_bf16_f32 v72, v134, v236
	v_cvt_pk_bf16_f32 v73, v135, v237
	global_store_dwordx2 v250, v[72:73], s[62:63]
	v_cvt_pk_bf16_f32 v74, v14, v15
	v_cvt_pk_bf16_f32 v75, v16, v17
	s_add_u32 s0, s62, 0x500000
	s_addc_u32 s1, s63, 0
	global_store_dwordx2 v250, v[74:75], s[0:1]
	v_cvt_pk_bf16_f32 v180, v152, v153
	v_cvt_pk_bf16_f32 v181, v154, v155
	s_add_u32 s0, s62, 0xa00000
	s_addc_u32 s1, s63, 0
	global_store_dwordx2 v250, v[180:181], s[0:1]
	v_cvt_pk_bf16_f32 v72, v138, v240
	v_cvt_pk_bf16_f32 v73, v139, v241
	s_add_u32 s0, s62, 0xf00000
	s_addc_u32 s1, s63, 0
	global_store_dwordx2 v250, v[72:73], s[0:1]
	v_cvt_pk_bf16_f32 v74, v148, v149
	v_cvt_pk_bf16_f32 v75, v150, v151
	s_add_u32 s0, s62, 0x1400000
	s_addc_u32 s1, s63, 0
	global_store_dwordx2 v250, v[74:75], s[0:1]
	v_cvt_pk_bf16_f32 v180, v18, v19
	v_cvt_pk_bf16_f32 v181, v20, v21
	s_add_u32 s0, s62, 0x1900000
	s_addc_u32 s1, s63, 0
	global_store_dwordx2 v250, v[180:181], s[0:1]
	v_cvt_pk_bf16_f32 v72, v156, v157
	v_cvt_pk_bf16_f32 v73, v158, v159
	s_lshl_b32 s0, s57, 9
	s_add_u32 s0, s42, s0
	s_addc_u32 s1, s43, 0
	global_store_dwordx2 v250, v[72:73], s[0:1]
	s_branch .LBB0_476
.Lprep_tok_d1:
	ds_read_b128 v[210:213], v251 offset:53248
	ds_read_b128 v[214:217], v251 offset:54272
	ds_read_b128 v[218:221], v251 offset:55296
	ds_read_b128 v[198:201], v251 offset:56320
	ds_read_b128 v[194:197], v251 offset:57344
	ds_read_b128 v[190:193], v251 offset:58368
	ds_read_b128 v[202:205], v251 offset:59392
	ds_read_b128 v[206:209], v251 offset:60416
	s_add_u32 s34, s34, 0x1e00000
	s_addc_u32 s35, s35, 0
	s_add_i32 s56, s53, 0
	s_cmpk_lt_i32 s56, 0x2000
	s_movk_i32 s0, 0x3ff
	s_cselect_b32 s0, 0xff, s0
	s_and_b32 s1, s56, s0
	s_cmp_lg_u32 s1, s0
	s_cselect_b32 s59, 1.0, 0
	s_cselect_b32 s1, 1, 0
	s_add_i32 s1, s56, s1
	s_mul_i32 s0, s56, 0x1d00
	s_add_u32 s76, s28, s0
	s_addc_u32 s77, s29, 0
	s_mul_i32 s0, s1, 0x1d00
	s_add_u32 s78, s28, s0
	s_addc_u32 s79, s29, 0
	global_load_dwordx2 v[222:223], v250, s[76:77] offset:0
	global_load_dwordx2 v[224:225], v250, s[76:77] offset:512
	global_load_dwordx2 v[226:227], v250, s[76:77] offset:1024
	global_load_dwordx2 v[228:229], v250, s[78:79] offset:0
	global_load_dwordx2 v[230:231], v250, s[78:79] offset:512
	global_load_dwordx2 v[232:233], v250, s[78:79] offset:1024
	s_lshl_b32 s0, s56, 9
	s_add_u32 s0, s42, s0
	s_addc_u32 s1, s43, 0
	global_load_dwordx2 v[234:235], v250, s[0:1]
	s_add_i32 s57, s53, 4
	s_cmpk_lt_i32 s57, 0x2000
	s_movk_i32 s0, 0x3ff
	s_cselect_b32 s0, 0xff, s0
	s_and_b32 s1, s57, s0
	s_cmp_lg_u32 s1, s0
	s_cselect_b32 s60, 1.0, 0
	s_cselect_b32 s1, 1, 0
	s_add_i32 s1, s57, s1
	s_mul_i32 s0, s57, 0x1d00
	s_add_u32 s80, s28, s0
	s_addc_u32 s81, s29, 0
	s_mul_i32 s0, s1, 0x1d00
	s_add_u32 s82, s28, s0
	s_addc_u32 s83, s29, 0
	global_load_dwordx2 v[236:237], v250, s[80:81] offset:0
	global_load_dwordx2 v[238:239], v250, s[80:81] offset:512
	global_load_dwordx2 v[240:241], v250, s[80:81] offset:1024
	global_load_dwordx2 v[242:243], v250, s[82:83] offset:0
	global_load_dwordx2 v[244:245], v250, s[82:83] offset:512
	global_load_dwordx2 v[246:247], v250, s[82:83] offset:1024
	s_lshl_b32 s0, s57, 9
	s_add_u32 s0, s42, s0
	s_addc_u32 s1, s43, 0
	global_load_dwordx2 v[248:249], v250, s[0:1]
	s_add_i32 s58, s53, 8
	s_cmpk_lt_i32 s58, 0x2000
	s_movk_i32 s0, 0x3ff
	s_cselect_b32 s0, 0xff, s0
	s_and_b32 s1, s58, s0
	s_cmp_lg_u32 s1, s0
	s_cselect_b32 s61, 1.0, 0
	s_cselect_b32 s1, 1, 0
	s_add_i32 s1, s58, s1
	s_mul_i32 s0, s58, 0x1d00
	s_add_u32 s84, s28, s0
	s_addc_u32 s85, s29, 0
	s_mul_i32 s0, s1, 0x1d00
	s_add_u32 s96, s28, s0
	s_addc_u32 s97, s29, 0
	global_load_dwordx2 v[0:1], v250, s[84:85] offset:0
	global_load_dwordx2 v[2:3], v250, s[84:85] offset:512
	global_load_dwordx2 v[4:5], v250, s[84:85] offset:1024
	global_load_dwordx2 v[6:7], v250, s[96:97] offset:0
	global_load_dwordx2 v[8:9], v250, s[96:97] offset:512
	global_load_dwordx2 v[10:11], v250, s[96:97] offset:1024
	s_lshl_b32 s0, s58, 9
	s_add_u32 s0, s42, s0
	s_addc_u32 s1, s43, 0
	global_load_dwordx2 v[12:13], v250, s[0:1]
	ds_read_b128 v[14:17], v31 offset:0
	ds_read_b128 v[18:21], v31 offset:20480
	ds_read_b128 v[22:25], v31 offset:4096
	ds_read_b128 v[26:29], v31 offset:24576
	s_waitcnt lgkmcnt(4)
	s_waitcnt vmcnt(14)
	v_lshlrev_b32_e32 v134, 16, v222
	v_and_b32_e32 v222, 0xffff0000, v222
	v_lshlrev_b32_e32 v135, 16, v223
	v_and_b32_e32 v223, 0xffff0000, v223
	v_lshlrev_b32_e32 v136, 16, v224
	v_and_b32_e32 v224, 0xffff0000, v224
	v_lshlrev_b32_e32 v137, 16, v225
	v_and_b32_e32 v225, 0xffff0000, v225
	v_lshlrev_b32_e32 v138, 16, v226
	v_and_b32_e32 v226, 0xffff0000, v226
	v_lshlrev_b32_e32 v139, 16, v227
	v_and_b32_e32 v227, 0xffff0000, v227
	v_lshlrev_b32_e32 v140, 16, v228
	v_and_b32_e32 v228, 0xffff0000, v228
	v_lshlrev_b32_e32 v141, 16, v229
	v_and_b32_e32 v229, 0xffff0000, v229
	v_lshlrev_b32_e32 v142, 16, v230
	v_and_b32_e32 v230, 0xffff0000, v230
	v_lshlrev_b32_e32 v143, 16, v231
	v_and_b32_e32 v231, 0xffff0000, v231
	v_lshlrev_b32_e32 v144, 16, v232
	v_and_b32_e32 v232, 0xffff0000, v232
	v_lshlrev_b32_e32 v145, 16, v233
	v_and_b32_e32 v233, 0xffff0000, v233
	v_lshlrev_b32_e32 v146, 16, v234
	v_and_b32_e32 v234, 0xffff0000, v234
	v_lshlrev_b32_e32 v147, 16, v235
	v_and_b32_e32 v235, 0xffff0000, v235
	v_fma_f32 v140, s59, v140, -v134
	v_fma_f32 v228, s59, v228, -v222
	v_fma_f32 v141, s59, v141, -v135
	v_fma_f32 v229, s59, v229, -v223
	v_fmac_f32_e32 v134, v210, v140
	v_fmac_f32_e32 v222, v211, v228
	v_fmac_f32_e32 v135, v212, v141
	v_fmac_f32_e32 v223, v213, v229
	v_fma_f32 v142, s59, v142, -v136
	v_fma_f32 v230, s59, v230, -v224
	v_fma_f32 v143, s59, v143, -v137
	v_fma_f32 v231, s59, v231, -v225
	v_fmac_f32_e32 v136, v214, v142
	v_fmac_f32_e32 v224, v215, v230
	v_fmac_f32_e32 v137, v216, v143
	v_fmac_f32_e32 v225, v217, v231
	v_fma_f32 v144, s59, v144, -v138
	v_fma_f32 v232, s59, v232, -v226
	v_fma_f32 v145, s59, v145, -v139
	v_fma_f32 v233, s59, v233, -v227
	v_fmac_f32_e32 v138, v218, v144
	v_fmac_f32_e32 v226, v219, v232
	v_fmac_f32_e32 v139, v220, v145
	v_fmac_f32_e32 v227, v221, v233
	v_mul_f32_e32 v148, v198, v136
	v_mul_f32_e32 v149, v199, v224
	v_mul_f32_e32 v150, v200, v137
	v_mul_f32_e32 v151, v201, v225
	v_mul_f32_e32 v176, v148, v148
	v_fmac_f32_e32 v176, v149, v149
	v_fmac_f32_e32 v176, v150, v150
	v_fmac_f32_e32 v176, v151, v151
	s_waitcnt lgkmcnt(2)
	v_mul_f32_e32 v194, 0xbfb8aa3b, v194
	v_mul_f32_e32 v195, 0xbfb8aa3b, v195
	v_mul_f32_e32 v196, 0xbfb8aa3b, v196
	v_mul_f32_e32 v197, 0xbfb8aa3b, v197
	v_mul_f32_e32 v190, 0xbfb8aa3b, v190
	v_mul_f32_e32 v191, 0xbfb8aa3b, v191
	v_mul_f32_e32 v192, 0xbfb8aa3b, v192
	v_mul_f32_e32 v193, 0xbfb8aa3b, v193
	v_fmamk_f32 v18, v18, 0xbfb8aa3b, v194
	v_fmamk_f32 v19, v19, 0xbfb8aa3b, v195
	v_fmamk_f32 v20, v20, 0xbfb8aa3b, v196
	v_fmamk_f32 v21, v21, 0xbfb8aa3b, v197
	v_add_f32_dpp v176, v176, v176 quad_perm:[1,0,3,2] row_mask:0xf bank_mask:0xf bound_ctrl:1
	v_exp_f32_e32 v18, v18
	v_exp_f32_e32 v19, v19
	v_exp_f32_e32 v20, v20
	v_exp_f32_e32 v21, v21
	v_add_f32_dpp v176, v176, v176 quad_perm:[2,3,0,1] row_mask:0xf bank_mask:0xf bound_ctrl:1
	v_add_f32_e32 v18, 1.0, v18
	v_add_f32_e32 v19, 1.0, v19
	v_add_f32_e32 v20, 1.0, v20
	v_add_f32_e32 v21, 1.0, v21
	v_add_f32_dpp v176, v176, v176 row_half_mirror row_mask:0xf bank_mask:0xf bound_ctrl:1
	v_rcp_f32_e32 v18, v18
	v_rcp_f32_e32 v19, v19
	v_rcp_f32_e32 v20, v20
	v_rcp_f32_e32 v21, v21
	v_add_f32_dpp v176, v176, v176 row_mirror row_mask:0xf bank_mask:0xf bound_ctrl:1
	v_fmamk_f32 v14, v14, 0xbfb8aa3b, v190
	v_fmamk_f32 v15, v15, 0xbfb8aa3b, v191
	v_fmamk_f32 v16, v16, 0xbfb8aa3b, v192
	v_fmamk_f32 v17, v17, 0xbfb8aa3b, v193
	v_sqrt_f32_e32 v176, v176
	v_exp_f32_e32 v14, v14
	v_exp_f32_e32 v15, v15
	v_exp_f32_e32 v16, v16
	v_exp_f32_e32 v17, v17
	v_max_f32_e32 v176, 0x2b8cbccc, v176
	v_add_f32_e32 v14, 1.0, v14
	v_add_f32_e32 v15, 1.0, v15
	v_add_f32_e32 v16, 1.0, v16
	v_add_f32_e32 v17, 1.0, v17
	v_rcp_f32_e32 v178, v176
	v_rcp_f32_e32 v14, v14
	v_rcp_f32_e32 v15, v15
	v_rcp_f32_e32 v16, v16
	v_rcp_f32_e32 v17, v17
	v_mul_f32_e32 v14, 0xbf60028a, v14
	v_mul_f32_e32 v15, 0xbf60028a, v15
	v_mul_f32_e32 v16, 0xbf60028a, v16
	v_mul_f32_e32 v17, 0xbf60028a, v17
	v_exp_f32_e32 v14, v14
	v_exp_f32_e32 v15, v15
	v_exp_f32_e32 v16, v16
	v_exp_f32_e32 v17, v17
	v_add_f32_e32 v152, -1.0, v18
	v_add_f32_e32 v153, -1.0, v19
	v_add_f32_e32 v154, -1.0, v20
	v_add_f32_e32 v155, -1.0, v21
	v_fma_f32 v152, v202, v152, 1.0
	v_fma_f32 v153, v203, v153, 1.0
	v_fma_f32 v154, v204, v154, 1.0
	v_fma_f32 v155, v205, v155, 1.0
	v_mul_f32_e32 v152, v136, v152
	v_mul_f32_e32 v153, v224, v153
	v_mul_f32_e32 v154, v137, v154
	v_mul_f32_e32 v155, v225, v155
	v_mul_f32_e32 v156, v134, v152
	v_mul_f32_e32 v157, v222, v153
	v_mul_f32_e32 v158, v135, v154
	v_mul_f32_e32 v159, v223, v155
	v_mul_f32_e32 v177, v206, v156
	v_fmac_f32_e32 v177, v207, v157
	v_fmac_f32_e32 v177, v208, v158
	v_fmac_f32_e32 v177, v209, v159
	v_mul_f32_e32 v148, v148, v178
	v_mul_f32_e32 v149, v149, v178
	v_add_f32_dpp v177, v177, v177 quad_perm:[1,0,3,2] row_mask:0xf bank_mask:0xf bound_ctrl:1
	v_mul_f32_e32 v150, v150, v178
	v_mul_f32_e32 v151, v151, v178
	v_add_f32_dpp v177, v177, v177 quad_perm:[2,3,0,1] row_mask:0xf bank_mask:0xf bound_ctrl:1
	v_mul_f32_e32 v18, v18, v148
	v_mul_f32_e32 v19, v19, v149
	v_add_f32_dpp v177, v177, v177 row_half_mirror row_mask:0xf bank_mask:0xf bound_ctrl:1
	v_mul_f32_e32 v20, v20, v150
	v_mul_f32_e32 v21, v21, v151
	v_add_f32_dpp v177, v177, v177 row_mirror row_mask:0xf bank_mask:0xf bound_ctrl:1
	s_lshl_b32 s0, s56, 9
	s_add_u32 s62, s34, s0
	s_addc_u32 s63, s35, 0
	v_fmac_f32_e32 v146, v138, v177
	v_fmac_f32_e32 v234, v226, v177
	v_fmac_f32_e32 v147, v139, v177
	v_fmac_f32_e32 v235, v227, v177
	v_cvt_pk_bf16_f32 v72, v134, v222
	v_cvt_pk_bf16_f32 v73, v135, v223
	global_store_dwordx2 v250, v[72:73], s[62:63]
	v_cvt_pk_bf16_f32 v74, v14, v15
	v_cvt_pk_bf16_f32 v75, v16, v17
	s_add_u32 s0, s62, 0x500000
	s_addc_u32 s1, s63, 0
	global_store_dwordx2 v250, v[74:75], s[0:1]
	v_cvt_pk_bf16_f32 v180, v152, v153
	v_cvt_pk_bf16_f32 v181, v154, v155
	s_add_u32 s0, s62, 0xa00000
	s_addc_u32 s1, s63, 0
	global_store_dwordx2 v250, v[180:181], s[0:1]
	v_cvt_pk_bf16_f32 v72, v138, v226
	v_cvt_pk_bf16_f32 v73, v139, v227
	s_add_u32 s0, s62, 0xf00000
	s_addc_u32 s1, s63, 0
	global_store_dwordx2 v250, v[72:73], s[0:1]
	v_cvt_pk_bf16_f32 v74, v148, v149
	v_cvt_pk_bf16_f32 v75, v150, v151
	s_add_u32 s0, s62, 0x1400000
	s_addc_u32 s1, s63, 0
	global_store_dwordx2 v250, v[74:75], s[0:1]
	v_cvt_pk_bf16_f32 v180, v18, v19
	v_cvt_pk_bf16_f32 v181, v20, v21
	s_add_u32 s0, s62, 0x1900000
	s_addc_u32 s1, s63, 0
	global_store_dwordx2 v250, v[180:181], s[0:1]
	v_cvt_pk_bf16_f32 v72, v146, v234
	v_cvt_pk_bf16_f32 v73, v147, v235
	s_lshl_b32 s0, s56, 9
	s_add_u32 s0, s42, s0
	s_addc_u32 s1, s43, 0
	global_store_dwordx2 v250, v[72:73], s[0:1]
	s_add_i32 s56, s53, 12
	s_cmpk_lt_i32 s56, 0x2000
	s_movk_i32 s0, 0x3ff
	s_cselect_b32 s0, 0xff, s0
	s_and_b32 s1, s56, s0
	s_cmp_lg_u32 s1, s0
	s_cselect_b32 s59, 1.0, 0
	s_cselect_b32 s1, 1, 0
	s_add_i32 s1, s56, s1
	s_mul_i32 s0, s56, 0x1d00
	s_add_u32 s76, s28, s0
	s_addc_u32 s77, s29, 0
	s_mul_i32 s0, s1, 0x1d00
	s_add_u32 s78, s28, s0
	s_addc_u32 s79, s29, 0
	global_load_dwordx2 v[222:223], v250, s[76:77] offset:0
	global_load_dwordx2 v[224:225], v250, s[76:77] offset:512
	global_load_dwordx2 v[226:227], v250, s[76:77] offset:1024
	global_load_dwordx2 v[228:229], v250, s[78:79] offset:0
	global_load_dwordx2 v[230:231], v250, s[78:79] offset:512
	global_load_dwordx2 v[232:233], v250, s[78:79] offset:1024
	s_lshl_b32 s0, s56, 9
	s_add_u32 s0, s42, s0
	s_addc_u32 s1, s43, 0
	global_load_dwordx2 v[234:235], v250, s[0:1]
	ds_read_b128 v[14:17], v31 offset:8192
	ds_read_b128 v[18:21], v31 offset:28672
	s_waitcnt vmcnt(21)
	v_lshlrev_b32_e32 v134, 16, v236
	v_and_b32_e32 v236, 0xffff0000, v236
	v_lshlrev_b32_e32 v135, 16, v237
	v_and_b32_e32 v237, 0xffff0000, v237
	v_lshlrev_b32_e32 v136, 16, v238
	v_and_b32_e32 v238, 0xffff0000, v238
	v_lshlrev_b32_e32 v137, 16, v239
	v_and_b32_e32 v239, 0xffff0000, v239
	v_lshlrev_b32_e32 v138, 16, v240
	v_and_b32_e32 v240, 0xffff0000, v240
	v_lshlrev_b32_e32 v139, 16, v241
	v_and_b32_e32 v241, 0xffff0000, v241
	v_lshlrev_b32_e32 v140, 16, v242
	v_and_b32_e32 v242, 0xffff0000, v242
	v_lshlrev_b32_e32 v141, 16, v243
	v_and_b32_e32 v243, 0xffff0000, v243
	v_lshlrev_b32_e32 v142, 16, v244
	v_and_b32_e32 v244, 0xffff0000, v244
	v_lshlrev_b32_e32 v143, 16, v245
	v_and_b32_e32 v245, 0xffff0000, v245
	v_lshlrev_b32_e32 v144, 16, v246
	v_and_b32_e32 v246, 0xffff0000, v246
	v_lshlrev_b32_e32 v145, 16, v247
	v_and_b32_e32 v247, 0xffff0000, v247
	v_lshlrev_b32_e32 v146, 16, v248
	v_and_b32_e32 v248, 0xffff0000, v248
	v_lshlrev_b32_e32 v147, 16, v249
	v_and_b32_e32 v249, 0xffff0000, v249
	v_fma_f32 v140, s60, v140, -v134
	v_fma_f32 v242, s60, v242, -v236
	v_fma_f32 v141, s60, v141, -v135
	v_fma_f32 v243, s60, v243, -v237
	v_fmac_f32_e32 v134, v210, v140
	v_fmac_f32_e32 v236, v211, v242
	v_fmac_f32_e32 v135, v212, v141
	v_fmac_f32_e32 v237, v213, v243
	v_fma_f32 v142, s60, v142, -v136
	v_fma_f32 v244, s60, v244, -v238
	v_fma_f32 v143, s60, v143, -v137
	v_fma_f32 v245, s60, v245, -v239
	v_fmac_f32_e32 v136, v214, v142
	v_fmac_f32_e32 v238, v215, v244
	v_fmac_f32_e32 v137, v216, v143
	v_fmac_f32_e32 v239, v217, v245
	v_fma_f32 v144, s60, v144, -v138
	v_fma_f32 v246, s60, v246, -v240
	v_fma_f32 v145, s60, v145, -v139
	v_fma_f32 v247, s60, v247, -v241
	v_fmac_f32_e32 v138, v218, v144
	v_fmac_f32_e32 v240, v219, v246
	v_fmac_f32_e32 v139, v220, v145
	v_fmac_f32_e32 v241, v221, v247
	v_mul_f32_e32 v148, v198, v136
	v_mul_f32_e32 v149, v199, v238
	v_mul_f32_e32 v150, v200, v137
	v_mul_f32_e32 v151, v201, v239
	v_mul_f32_e32 v176, v148, v148
	v_fmac_f32_e32 v176, v149, v149
	v_fmac_f32_e32 v176, v150, v150
	v_fmac_f32_e32 v176, v151, v151
	s_waitcnt lgkmcnt(2)
	v_fmamk_f32 v26, v26, 0xbfb8aa3b, v194
	v_fmamk_f32 v27, v27, 0xbfb8aa3b, v195
	v_fmamk_f32 v28, v28, 0xbfb8aa3b, v196
	v_fmamk_f32 v29, v29, 0xbfb8aa3b, v197
	v_add_f32_dpp v176, v176, v176 quad_perm:[1,0,3,2] row_mask:0xf bank_mask:0xf bound_ctrl:1
	v_exp_f32_e32 v26, v26
	v_exp_f32_e32 v27, v27
	v_exp_f32_e32 v28, v28
	v_exp_f32_e32 v29, v29
	v_add_f32_dpp v176, v176, v176 quad_perm:[2,3,0,1] row_mask:0xf bank_mask:0xf bound_ctrl:1
	v_add_f32_e32 v26, 1.0, v26
	v_add_f32_e32 v27, 1.0, v27
	v_add_f32_e32 v28, 1.0, v28
	v_add_f32_e32 v29, 1.0, v29
	v_add_f32_dpp v176, v176, v176 row_half_mirror row_mask:0xf bank_mask:0xf bound_ctrl:1
	v_rcp_f32_e32 v26, v26
	v_rcp_f32_e32 v27, v27
	v_rcp_f32_e32 v28, v28
	v_rcp_f32_e32 v29, v29
	v_add_f32_dpp v176, v176, v176 row_mirror row_mask:0xf bank_mask:0xf bound_ctrl:1
	v_fmamk_f32 v22, v22, 0xbfb8aa3b, v190
	v_fmamk_f32 v23, v23, 0xbfb8aa3b, v191
	v_fmamk_f32 v24, v24, 0xbfb8aa3b, v192
	v_fmamk_f32 v25, v25, 0xbfb8aa3b, v193
	v_sqrt_f32_e32 v176, v176
	v_exp_f32_e32 v22, v22
	v_exp_f32_e32 v23, v23
	v_exp_f32_e32 v24, v24
	v_exp_f32_e32 v25, v25
	v_max_f32_e32 v176, 0x2b8cbccc, v176
	v_add_f32_e32 v22, 1.0, v22
	v_add_f32_e32 v23, 1.0, v23
	v_add_f32_e32 v24, 1.0, v24
	v_add_f32_e32 v25, 1.0, v25
	v_rcp_f32_e32 v178, v176
	v_rcp_f32_e32 v22, v22
	v_rcp_f32_e32 v23, v23
	v_rcp_f32_e32 v24, v24
	v_rcp_f32_e32 v25, v25
	v_mul_f32_e32 v22, 0xbf60028a, v22
	v_mul_f32_e32 v23, 0xbf60028a, v23
	v_mul_f32_e32 v24, 0xbf60028a, v24
	v_mul_f32_e32 v25, 0xbf60028a, v25
	v_exp_f32_e32 v22, v22
	v_exp_f32_e32 v23, v23
	v_exp_f32_e32 v24, v24
	v_exp_f32_e32 v25, v25
	v_add_f32_e32 v152, -1.0, v26
	v_add_f32_e32 v153, -1.0, v27
	v_add_f32_e32 v154, -1.0, v28
	v_add_f32_e32 v155, -1.0, v29
	v_fma_f32 v152, v202, v152, 1.0
	v_fma_f32 v153, v203, v153, 1.0
	v_fma_f32 v154, v204, v154, 1.0
	v_fma_f32 v155, v205, v155, 1.0
	v_mul_f32_e32 v152, v136, v152
	v_mul_f32_e32 v153, v238, v153
	v_mul_f32_e32 v154, v137, v154
	v_mul_f32_e32 v155, v239, v155
	v_mul_f32_e32 v156, v134, v152
	v_mul_f32_e32 v157, v236, v153
	v_mul_f32_e32 v158, v135, v154
	v_mul_f32_e32 v159, v237, v155
	v_mul_f32_e32 v177, v206, v156
	v_fmac_f32_e32 v177, v207, v157
	v_fmac_f32_e32 v177, v208, v158
	v_fmac_f32_e32 v177, v209, v159
	v_mul_f32_e32 v148, v148, v178
	v_mul_f32_e32 v149, v149, v178
	v_add_f32_dpp v177, v177, v177 quad_perm:[1,0,3,2] row_mask:0xf bank_mask:0xf bound_ctrl:1
	v_mul_f32_e32 v150, v150, v178
	v_mul_f32_e32 v151, v151, v178
	v_add_f32_dpp v177, v177, v177 quad_perm:[2,3,0,1] row_mask:0xf bank_mask:0xf bound_ctrl:1
	v_mul_f32_e32 v26, v26, v148
	v_mul_f32_e32 v27, v27, v149
	v_add_f32_dpp v177, v177, v177 row_half_mirror row_mask:0xf bank_mask:0xf bound_ctrl:1
	v_mul_f32_e32 v28, v28, v150
	v_mul_f32_e32 v29, v29, v151
	v_add_f32_dpp v177, v177, v177 row_mirror row_mask:0xf bank_mask:0xf bound_ctrl:1
	s_lshl_b32 s0, s57, 9
	s_add_u32 s62, s34, s0
	s_addc_u32 s63, s35, 0
	v_fmac_f32_e32 v146, v138, v177
	v_fmac_f32_e32 v248, v240, v177
	v_fmac_f32_e32 v147, v139, v177
	v_fmac_f32_e32 v249, v241, v177
	v_cvt_pk_bf16_f32 v72, v134, v236
	v_cvt_pk_bf16_f32 v73, v135, v237
	global_store_dwordx2 v250, v[72:73], s[62:63]
	v_cvt_pk_bf16_f32 v74, v22, v23
	v_cvt_pk_bf16_f32 v75, v24, v25
	s_add_u32 s0, s62, 0x500000
	s_addc_u32 s1, s63, 0
	global_store_dwordx2 v250, v[74:75], s[0:1]
	v_cvt_pk_bf16_f32 v180, v152, v153
	v_cvt_pk_bf16_f32 v181, v154, v155
	s_add_u32 s0, s62, 0xa00000
	s_addc_u32 s1, s63, 0
	global_store_dwordx2 v250, v[180:181], s[0:1]
	v_cvt_pk_bf16_f32 v72, v138, v240
	v_cvt_pk_bf16_f32 v73, v139, v241
	s_add_u32 s0, s62, 0xf00000
	s_addc_u32 s1, s63, 0
	global_store_dwordx2 v250, v[72:73], s[0:1]
	v_cvt_pk_bf16_f32 v74, v148, v149
	v_cvt_pk_bf16_f32 v75, v150, v151
	s_add_u32 s0, s62, 0x1400000
	s_addc_u32 s1, s63, 0
	global_store_dwordx2 v250, v[74:75], s[0:1]
	v_cvt_pk_bf16_f32 v180, v26, v27
	v_cvt_pk_bf16_f32 v181, v28, v29
	s_add_u32 s0, s62, 0x1900000
	s_addc_u32 s1, s63, 0
	global_store_dwordx2 v250, v[180:181], s[0:1]
	v_cvt_pk_bf16_f32 v72, v146, v248
	v_cvt_pk_bf16_f32 v73, v147, v249
	s_lshl_b32 s0, s57, 9
	s_add_u32 s0, s42, s0
	s_addc_u32 s1, s43, 0
	global_store_dwordx2 v250, v[72:73], s[0:1]
	s_add_i32 s57, s53, 16
	s_cmpk_lt_i32 s57, 0x2000
	s_movk_i32 s0, 0x3ff
	s_cselect_b32 s0, 0xff, s0
	s_and_b32 s1, s57, s0
	s_cmp_lg_u32 s1, s0
	s_cselect_b32 s60, 1.0, 0
	s_cselect_b32 s1, 1, 0
	s_add_i32 s1, s57, s1
	s_mul_i32 s0, s57, 0x1d00
	s_add_u32 s80, s28, s0
	s_addc_u32 s81, s29, 0
	s_mul_i32 s0, s1, 0x1d00
	s_add_u32 s82, s28, s0
	s_addc_u32 s83, s29, 0
	global_load_dwordx2 v[236:237], v250, s[80:81] offset:0
	global_load_dwordx2 v[238:239], v250, s[80:81] offset:512
	global_load_dwordx2 v[240:241], v250, s[80:81] offset:1024
	global_load_dwordx2 v[242:243], v250, s[82:83] offset:0
	global_load_dwordx2 v[244:245], v250, s[82:83] offset:512
	global_load_dwordx2 v[246:247], v250, s[82:83] offset:1024
	s_lshl_b32 s0, s57, 9
	s_add_u32 s0, s42, s0
	s_addc_u32 s1, s43, 0
	global_load_dwordx2 v[248:249], v250, s[0:1]
	ds_read_b128 v[22:25], v31 offset:12288
	ds_read_b128 v[26:29], v31 offset:32768
	s_waitcnt vmcnt(28)
	v_lshlrev_b32_e32 v134, 16, v0
	v_and_b32_e32 v0, 0xffff0000, v0
	v_lshlrev_b32_e32 v135, 16, v1
	v_and_b32_e32 v1, 0xffff0000, v1
	v_lshlrev_b32_e32 v136, 16, v2
	v_and_b32_e32 v2, 0xffff0000, v2
	v_lshlrev_b32_e32 v137, 16, v3
	v_and_b32_e32 v3, 0xffff0000, v3
	v_lshlrev_b32_e32 v138, 16, v4
	v_and_b32_e32 v4, 0xffff0000, v4
	v_lshlrev_b32_e32 v139, 16, v5
	v_and_b32_e32 v5, 0xffff0000, v5
	v_lshlrev_b32_e32 v140, 16, v6
	v_and_b32_e32 v6, 0xffff0000, v6
	v_lshlrev_b32_e32 v141, 16, v7
	v_and_b32_e32 v7, 0xffff0000, v7
	v_lshlrev_b32_e32 v142, 16, v8
	v_and_b32_e32 v8, 0xffff0000, v8
	v_lshlrev_b32_e32 v143, 16, v9
	v_and_b32_e32 v9, 0xffff0000, v9
	v_lshlrev_b32_e32 v144, 16, v10
	v_and_b32_e32 v10, 0xffff0000, v10
	v_lshlrev_b32_e32 v145, 16, v11
	v_and_b32_e32 v11, 0xffff0000, v11
	v_lshlrev_b32_e32 v146, 16, v12
	v_and_b32_e32 v12, 0xffff0000, v12
	v_lshlrev_b32_e32 v147, 16, v13
	v_and_b32_e32 v13, 0xffff0000, v13
	v_fma_f32 v140, s61, v140, -v134
	v_fma_f32 v6, s61, v6, -v0
	v_fma_f32 v141, s61, v141, -v135
	v_fma_f32 v7, s61, v7, -v1
	v_fmac_f32_e32 v134, v210, v140
	v_fmac_f32_e32 v0, v211, v6
	v_fmac_f32_e32 v135, v212, v141
	v_fmac_f32_e32 v1, v213, v7
	v_fma_f32 v142, s61, v142, -v136
	v_fma_f32 v8, s61, v8, -v2
	v_fma_f32 v143, s61, v143, -v137
	v_fma_f32 v9, s61, v9, -v3
	v_fmac_f32_e32 v136, v214, v142
	v_fmac_f32_e32 v2, v215, v8
	v_fmac_f32_e32 v137, v216, v143
	v_fmac_f32_e32 v3, v217, v9
	v_fma_f32 v144, s61, v144, -v138
	v_fma_f32 v10, s61, v10, -v4
	v_fma_f32 v145, s61, v145, -v139
	v_fma_f32 v11, s61, v11, -v5
	v_fmac_f32_e32 v138, v218, v144
	v_fmac_f32_e32 v4, v219, v10
	v_fmac_f32_e32 v139, v220, v145
	v_fmac_f32_e32 v5, v221, v11
	v_mul_f32_e32 v148, v198, v136
	v_mul_f32_e32 v149, v199, v2
	v_mul_f32_e32 v150, v200, v137
	v_mul_f32_e32 v151, v201, v3
	v_mul_f32_e32 v176, v148, v148
	v_fmac_f32_e32 v176, v149, v149
	v_fmac_f32_e32 v176, v150, v150
	v_fmac_f32_e32 v176, v151, v151
	s_waitcnt lgkmcnt(2)
	v_fmamk_f32 v18, v18, 0xbfb8aa3b, v194
	v_fmamk_f32 v19, v19, 0xbfb8aa3b, v195
	v_fmamk_f32 v20, v20, 0xbfb8aa3b, v196
	v_fmamk_f32 v21, v21, 0xbfb8aa3b, v197
	v_add_f32_dpp v176, v176, v176 quad_perm:[1,0,3,2] row_mask:0xf bank_mask:0xf bound_ctrl:1
	v_exp_f32_e32 v18, v18
	v_exp_f32_e32 v19, v19
	v_exp_f32_e32 v20, v20
	v_exp_f32_e32 v21, v21
	v_add_f32_dpp v176, v176, v176 quad_perm:[2,3,0,1] row_mask:0xf bank_mask:0xf bound_ctrl:1
	v_add_f32_e32 v18, 1.0, v18
	v_add_f32_e32 v19, 1.0, v19
	v_add_f32_e32 v20, 1.0, v20
	v_add_f32_e32 v21, 1.0, v21
	v_add_f32_dpp v176, v176, v176 row_half_mirror row_mask:0xf bank_mask:0xf bound_ctrl:1
	v_rcp_f32_e32 v18, v18
	v_rcp_f32_e32 v19, v19
	v_rcp_f32_e32 v20, v20
	v_rcp_f32_e32 v21, v21
	v_add_f32_dpp v176, v176, v176 row_mirror row_mask:0xf bank_mask:0xf bound_ctrl:1
	v_fmamk_f32 v14, v14, 0xbfb8aa3b, v190
	v_fmamk_f32 v15, v15, 0xbfb8aa3b, v191
	v_fmamk_f32 v16, v16, 0xbfb8aa3b, v192
	v_fmamk_f32 v17, v17, 0xbfb8aa3b, v193
	v_sqrt_f32_e32 v176, v176
	v_exp_f32_e32 v14, v14
	v_exp_f32_e32 v15, v15
	v_exp_f32_e32 v16, v16
	v_exp_f32_e32 v17, v17
	v_max_f32_e32 v176, 0x2b8cbccc, v176
	v_add_f32_e32 v14, 1.0, v14
	v_add_f32_e32 v15, 1.0, v15
	v_add_f32_e32 v16, 1.0, v16
	v_add_f32_e32 v17, 1.0, v17
	v_rcp_f32_e32 v178, v176
	v_rcp_f32_e32 v14, v14
	v_rcp_f32_e32 v15, v15
	v_rcp_f32_e32 v16, v16
	v_rcp_f32_e32 v17, v17
	v_mul_f32_e32 v14, 0xbf60028a, v14
	v_mul_f32_e32 v15, 0xbf60028a, v15
	v_mul_f32_e32 v16, 0xbf60028a, v16
	v_mul_f32_e32 v17, 0xbf60028a, v17
	v_exp_f32_e32 v14, v14
	v_exp_f32_e32 v15, v15
	v_exp_f32_e32 v16, v16
	v_exp_f32_e32 v17, v17
	v_add_f32_e32 v152, -1.0, v18
	v_add_f32_e32 v153, -1.0, v19
	v_add_f32_e32 v154, -1.0, v20
	v_add_f32_e32 v155, -1.0, v21
	v_fma_f32 v152, v202, v152, 1.0
	v_fma_f32 v153, v203, v153, 1.0
	v_fma_f32 v154, v204, v154, 1.0
	v_fma_f32 v155, v205, v155, 1.0
	v_mul_f32_e32 v152, v136, v152
	v_mul_f32_e32 v153, v2, v153
	v_mul_f32_e32 v154, v137, v154
	v_mul_f32_e32 v155, v3, v155
	v_mul_f32_e32 v156, v134, v152
	v_mul_f32_e32 v157, v0, v153
	v_mul_f32_e32 v158, v135, v154
	v_mul_f32_e32 v159, v1, v155
	v_mul_f32_e32 v177, v206, v156
	v_fmac_f32_e32 v177, v207, v157
	v_fmac_f32_e32 v177, v208, v158
	v_fmac_f32_e32 v177, v209, v159
	v_mul_f32_e32 v148, v148, v178
	v_mul_f32_e32 v149, v149, v178
	v_add_f32_dpp v177, v177, v177 quad_perm:[1,0,3,2] row_mask:0xf bank_mask:0xf bound_ctrl:1
	v_mul_f32_e32 v150, v150, v178
	v_mul_f32_e32 v151, v151, v178
	v_add_f32_dpp v177, v177, v177 quad_perm:[2,3,0,1] row_mask:0xf bank_mask:0xf bound_ctrl:1
	v_mul_f32_e32 v18, v18, v148
	v_mul_f32_e32 v19, v19, v149
	v_add_f32_dpp v177, v177, v177 row_half_mirror row_mask:0xf bank_mask:0xf bound_ctrl:1
	v_mul_f32_e32 v20, v20, v150
	v_mul_f32_e32 v21, v21, v151
	v_add_f32_dpp v177, v177, v177 row_mirror row_mask:0xf bank_mask:0xf bound_ctrl:1
	s_lshl_b32 s0, s58, 9
	s_add_u32 s62, s34, s0
	s_addc_u32 s63, s35, 0
	v_fmac_f32_e32 v146, v138, v177
	v_fmac_f32_e32 v12, v4, v177
	v_fmac_f32_e32 v147, v139, v177
	v_fmac_f32_e32 v13, v5, v177
	v_cvt_pk_bf16_f32 v72, v134, v0
	v_cvt_pk_bf16_f32 v73, v135, v1
	global_store_dwordx2 v250, v[72:73], s[62:63]
	v_cvt_pk_bf16_f32 v74, v14, v15
	v_cvt_pk_bf16_f32 v75, v16, v17
	s_add_u32 s0, s62, 0x500000
	s_addc_u32 s1, s63, 0
	global_store_dwordx2 v250, v[74:75], s[0:1]
	v_cvt_pk_bf16_f32 v180, v152, v153
	v_cvt_pk_bf16_f32 v181, v154, v155
	s_add_u32 s0, s62, 0xa00000
	s_addc_u32 s1, s63, 0
	global_store_dwordx2 v250, v[180:181], s[0:1]
	v_cvt_pk_bf16_f32 v72, v138, v4
	v_cvt_pk_bf16_f32 v73, v139, v5
	s_add_u32 s0, s62, 0xf00000
	s_addc_u32 s1, s63, 0
	global_store_dwordx2 v250, v[72:73], s[0:1]
	v_cvt_pk_bf16_f32 v74, v148, v149
	v_cvt_pk_bf16_f32 v75, v150, v151
	s_add_u32 s0, s62, 0x1400000
	s_addc_u32 s1, s63, 0
	global_store_dwordx2 v250, v[74:75], s[0:1]
	v_cvt_pk_bf16_f32 v180, v18, v19
	v_cvt_pk_bf16_f32 v181, v20, v21
	s_add_u32 s0, s62, 0x1900000
	s_addc_u32 s1, s63, 0
	global_store_dwordx2 v250, v[180:181], s[0:1]
	v_cvt_pk_bf16_f32 v72, v146, v12
	v_cvt_pk_bf16_f32 v73, v147, v13
	s_lshl_b32 s0, s58, 9
	s_add_u32 s0, s42, s0
	s_addc_u32 s1, s43, 0
	global_store_dwordx2 v250, v[72:73], s[0:1]
	ds_read_b128 v[14:17], v31 offset:16384
	ds_read_b128 v[18:21], v31 offset:36864
	s_waitcnt vmcnt(21)
	v_lshlrev_b32_e32 v134, 16, v222
	v_and_b32_e32 v222, 0xffff0000, v222
	v_lshlrev_b32_e32 v135, 16, v223
	v_and_b32_e32 v223, 0xffff0000, v223
	v_lshlrev_b32_e32 v136, 16, v224
	v_and_b32_e32 v224, 0xffff0000, v224
	v_lshlrev_b32_e32 v137, 16, v225
	v_and_b32_e32 v225, 0xffff0000, v225
	v_lshlrev_b32_e32 v138, 16, v226
	v_and_b32_e32 v226, 0xffff0000, v226
	v_lshlrev_b32_e32 v139, 16, v227
	v_and_b32_e32 v227, 0xffff0000, v227
	v_lshlrev_b32_e32 v140, 16, v228
	v_and_b32_e32 v228, 0xffff0000, v228
	v_lshlrev_b32_e32 v141, 16, v229
	v_and_b32_e32 v229, 0xffff0000, v229
	v_lshlrev_b32_e32 v142, 16, v230
	v_and_b32_e32 v230, 0xffff0000, v230
	v_lshlrev_b32_e32 v143, 16, v231
	v_and_b32_e32 v231, 0xffff0000, v231
	v_lshlrev_b32_e32 v144, 16, v232
	v_and_b32_e32 v232, 0xffff0000, v232
	v_lshlrev_b32_e32 v145, 16, v233
	v_and_b32_e32 v233, 0xffff0000, v233
	v_lshlrev_b32_e32 v146, 16, v234
	v_and_b32_e32 v234, 0xffff0000, v234
	v_lshlrev_b32_e32 v147, 16, v235
	v_and_b32_e32 v235, 0xffff0000, v235
	v_fma_f32 v140, s59, v140, -v134
	v_fma_f32 v228, s59, v228, -v222
	v_fma_f32 v141, s59, v141, -v135
	v_fma_f32 v229, s59, v229, -v223
	v_fmac_f32_e32 v134, v210, v140
	v_fmac_f32_e32 v222, v211, v228
	v_fmac_f32_e32 v135, v212, v141
	v_fmac_f32_e32 v223, v213, v229
	v_fma_f32 v142, s59, v142, -v136
	v_fma_f32 v230, s59, v230, -v224
	v_fma_f32 v143, s59, v143, -v137
	v_fma_f32 v231, s59, v231, -v225
	v_fmac_f32_e32 v136, v214, v142
	v_fmac_f32_e32 v224, v215, v230
	v_fmac_f32_e32 v137, v216, v143
	v_fmac_f32_e32 v225, v217, v231
	v_fma_f32 v144, s59, v144, -v138
	v_fma_f32 v232, s59, v232, -v226
	v_fma_f32 v145, s59, v145, -v139
	v_fma_f32 v233, s59, v233, -v227
	v_fmac_f32_e32 v138, v218, v144
	v_fmac_f32_e32 v226, v219, v232
	v_fmac_f32_e32 v139, v220, v145
	v_fmac_f32_e32 v227, v221, v233
	v_mul_f32_e32 v148, v198, v136
	v_mul_f32_e32 v149, v199, v224
	v_mul_f32_e32 v150, v200, v137
	v_mul_f32_e32 v151, v201, v225
	v_mul_f32_e32 v176, v148, v148
	v_fmac_f32_e32 v176, v149, v149
	v_fmac_f32_e32 v176, v150, v150
	v_fmac_f32_e32 v176, v151, v151
	s_waitcnt lgkmcnt(2)
	v_fmamk_f32 v26, v26, 0xbfb8aa3b, v194
	v_fmamk_f32 v27, v27, 0xbfb8aa3b, v195
	v_fmamk_f32 v28, v28, 0xbfb8aa3b, v196
	v_fmamk_f32 v29, v29, 0xbfb8aa3b, v197
	v_add_f32_dpp v176, v176, v176 quad_perm:[1,0,3,2] row_mask:0xf bank_mask:0xf bound_ctrl:1
	v_exp_f32_e32 v26, v26
	v_exp_f32_e32 v27, v27
	v_exp_f32_e32 v28, v28
	v_exp_f32_e32 v29, v29
	v_add_f32_dpp v176, v176, v176 quad_perm:[2,3,0,1] row_mask:0xf bank_mask:0xf bound_ctrl:1
	v_add_f32_e32 v26, 1.0, v26
	v_add_f32_e32 v27, 1.0, v27
	v_add_f32_e32 v28, 1.0, v28
	v_add_f32_e32 v29, 1.0, v29
	v_add_f32_dpp v176, v176, v176 row_half_mirror row_mask:0xf bank_mask:0xf bound_ctrl:1
	v_rcp_f32_e32 v26, v26
	v_rcp_f32_e32 v27, v27
	v_rcp_f32_e32 v28, v28
	v_rcp_f32_e32 v29, v29
	v_add_f32_dpp v176, v176, v176 row_mirror row_mask:0xf bank_mask:0xf bound_ctrl:1
	v_fmamk_f32 v22, v22, 0xbfb8aa3b, v190
	v_fmamk_f32 v23, v23, 0xbfb8aa3b, v191
	v_fmamk_f32 v24, v24, 0xbfb8aa3b, v192
	v_fmamk_f32 v25, v25, 0xbfb8aa3b, v193
	v_sqrt_f32_e32 v176, v176
	v_exp_f32_e32 v22, v22
	v_exp_f32_e32 v23, v23
	v_exp_f32_e32 v24, v24
	v_exp_f32_e32 v25, v25
	v_max_f32_e32 v176, 0x2b8cbccc, v176
	v_add_f32_e32 v22, 1.0, v22
	v_add_f32_e32 v23, 1.0, v23
	v_add_f32_e32 v24, 1.0, v24
	v_add_f32_e32 v25, 1.0, v25
	v_rcp_f32_e32 v178, v176
	v_rcp_f32_e32 v22, v22
	v_rcp_f32_e32 v23, v23
	v_rcp_f32_e32 v24, v24
	v_rcp_f32_e32 v25, v25
	v_mul_f32_e32 v22, 0xbf60028a, v22
	v_mul_f32_e32 v23, 0xbf60028a, v23
	v_mul_f32_e32 v24, 0xbf60028a, v24
	v_mul_f32_e32 v25, 0xbf60028a, v25
	v_exp_f32_e32 v22, v22
	v_exp_f32_e32 v23, v23
	v_exp_f32_e32 v24, v24
	v_exp_f32_e32 v25, v25
	v_add_f32_e32 v152, -1.0, v26
	v_add_f32_e32 v153, -1.0, v27
	v_add_f32_e32 v154, -1.0, v28
	v_add_f32_e32 v155, -1.0, v29
	v_fma_f32 v152, v202, v152, 1.0
	v_fma_f32 v153, v203, v153, 1.0
	v_fma_f32 v154, v204, v154, 1.0
	v_fma_f32 v155, v205, v155, 1.0
	v_mul_f32_e32 v152, v136, v152
	v_mul_f32_e32 v153, v224, v153
	v_mul_f32_e32 v154, v137, v154
	v_mul_f32_e32 v155, v225, v155
	v_mul_f32_e32 v156, v134, v152
	v_mul_f32_e32 v157, v222, v153
	v_mul_f32_e32 v158, v135, v154
	v_mul_f32_e32 v159, v223, v155
	v_mul_f32_e32 v177, v206, v156
	v_fmac_f32_e32 v177, v207, v157
	v_fmac_f32_e32 v177, v208, v158
	v_fmac_f32_e32 v177, v209, v159
	v_mul_f32_e32 v148, v148, v178
	v_mul_f32_e32 v149, v149, v178
	v_add_f32_dpp v177, v177, v177 quad_perm:[1,0,3,2] row_mask:0xf bank_mask:0xf bound_ctrl:1
	v_mul_f32_e32 v150, v150, v178
	v_mul_f32_e32 v151, v151, v178
	v_add_f32_dpp v177, v177, v177 quad_perm:[2,3,0,1] row_mask:0xf bank_mask:0xf bound_ctrl:1
	v_mul_f32_e32 v26, v26, v148
	v_mul_f32_e32 v27, v27, v149
	v_add_f32_dpp v177, v177, v177 row_half_mirror row_mask:0xf bank_mask:0xf bound_ctrl:1
	v_mul_f32_e32 v28, v28, v150
	v_mul_f32_e32 v29, v29, v151
	v_add_f32_dpp v177, v177, v177 row_mirror row_mask:0xf bank_mask:0xf bound_ctrl:1
	s_lshl_b32 s0, s56, 9
	s_add_u32 s62, s34, s0
	s_addc_u32 s63, s35, 0
	v_fmac_f32_e32 v146, v138, v177
	v_fmac_f32_e32 v234, v226, v177
	v_fmac_f32_e32 v147, v139, v177
	v_fmac_f32_e32 v235, v227, v177
	v_cvt_pk_bf16_f32 v72, v134, v222
	v_cvt_pk_bf16_f32 v73, v135, v223
	global_store_dwordx2 v250, v[72:73], s[62:63]
	v_cvt_pk_bf16_f32 v74, v22, v23
	v_cvt_pk_bf16_f32 v75, v24, v25
	s_add_u32 s0, s62, 0x500000
	s_addc_u32 s1, s63, 0
	global_store_dwordx2 v250, v[74:75], s[0:1]
	v_cvt_pk_bf16_f32 v180, v152, v153
	v_cvt_pk_bf16_f32 v181, v154, v155
	s_add_u32 s0, s62, 0xa00000
	s_addc_u32 s1, s63, 0
	global_store_dwordx2 v250, v[180:181], s[0:1]
	v_cvt_pk_bf16_f32 v72, v138, v226
	v_cvt_pk_bf16_f32 v73, v139, v227
	s_add_u32 s0, s62, 0xf00000
	s_addc_u32 s1, s63, 0
	global_store_dwordx2 v250, v[72:73], s[0:1]
	v_cvt_pk_bf16_f32 v74, v148, v149
	v_cvt_pk_bf16_f32 v75, v150, v151
	s_add_u32 s0, s62, 0x1400000
	s_addc_u32 s1, s63, 0
	global_store_dwordx2 v250, v[74:75], s[0:1]
	v_cvt_pk_bf16_f32 v180, v26, v27
	v_cvt_pk_bf16_f32 v181, v28, v29
	s_add_u32 s0, s62, 0x1900000
	s_addc_u32 s1, s63, 0
	global_store_dwordx2 v250, v[180:181], s[0:1]
	v_cvt_pk_bf16_f32 v72, v146, v234
	v_cvt_pk_bf16_f32 v73, v147, v235
	s_lshl_b32 s0, s56, 9
	s_add_u32 s0, s42, s0
	s_addc_u32 s1, s43, 0
	global_store_dwordx2 v250, v[72:73], s[0:1]
	s_waitcnt vmcnt(14)
	v_lshlrev_b32_e32 v134, 16, v236
	v_and_b32_e32 v236, 0xffff0000, v236
	v_lshlrev_b32_e32 v135, 16, v237
	v_and_b32_e32 v237, 0xffff0000, v237
	v_lshlrev_b32_e32 v136, 16, v238
	v_and_b32_e32 v238, 0xffff0000, v238
	v_lshlrev_b32_e32 v137, 16, v239
	v_and_b32_e32 v239, 0xffff0000, v239
	v_lshlrev_b32_e32 v138, 16, v240
	v_and_b32_e32 v240, 0xffff0000, v240
	v_lshlrev_b32_e32 v139, 16, v241
	v_and_b32_e32 v241, 0xffff0000, v241
	v_lshlrev_b32_e32 v140, 16, v242
	v_and_b32_e32 v242, 0xffff0000, v242
	v_lshlrev_b32_e32 v141, 16, v243
	v_and_b32_e32 v243, 0xffff0000, v243
	v_lshlrev_b32_e32 v142, 16, v244
	v_and_b32_e32 v244, 0xffff0000, v244
	v_lshlrev_b32_e32 v143, 16, v245
	v_and_b32_e32 v245, 0xffff0000, v245
	v_lshlrev_b32_e32 v144, 16, v246
	v_and_b32_e32 v246, 0xffff0000, v246
	v_lshlrev_b32_e32 v145, 16, v247
	v_and_b32_e32 v247, 0xffff0000, v247
	v_lshlrev_b32_e32 v146, 16, v248
	v_and_b32_e32 v248, 0xffff0000, v248
	v_lshlrev_b32_e32 v147, 16, v249
	v_and_b32_e32 v249, 0xffff0000, v249
	v_fma_f32 v140, s60, v140, -v134
	v_fma_f32 v242, s60, v242, -v236
	v_fma_f32 v141, s60, v141, -v135
	v_fma_f32 v243, s60, v243, -v237
	v_fmac_f32_e32 v134, v210, v140
	v_fmac_f32_e32 v236, v211, v242
	v_fmac_f32_e32 v135, v212, v141
	v_fmac_f32_e32 v237, v213, v243
	v_fma_f32 v142, s60, v142, -v136
	v_fma_f32 v244, s60, v244, -v238
	v_fma_f32 v143, s60, v143, -v137
	v_fma_f32 v245, s60, v245, -v239
	v_fmac_f32_e32 v136, v214, v142
	v_fmac_f32_e32 v238, v215, v244
	v_fmac_f32_e32 v137, v216, v143
	v_fmac_f32_e32 v239, v217, v245
	v_fma_f32 v144, s60, v144, -v138
	v_fma_f32 v246, s60, v246, -v240
	v_fma_f32 v145, s60, v145, -v139
	v_fma_f32 v247, s60, v247, -v241
	v_fmac_f32_e32 v138, v218, v144
	v_fmac_f32_e32 v240, v219, v246
	v_fmac_f32_e32 v139, v220, v145
	v_fmac_f32_e32 v241, v221, v247
	v_mul_f32_e32 v148, v198, v136
	v_mul_f32_e32 v149, v199, v238
	v_mul_f32_e32 v150, v200, v137
	v_mul_f32_e32 v151, v201, v239
	v_mul_f32_e32 v176, v148, v148
	v_fmac_f32_e32 v176, v149, v149
	v_fmac_f32_e32 v176, v150, v150
	v_fmac_f32_e32 v176, v151, v151
	s_waitcnt lgkmcnt(0)
	v_fmamk_f32 v18, v18, 0xbfb8aa3b, v194
	v_fmamk_f32 v19, v19, 0xbfb8aa3b, v195
	v_fmamk_f32 v20, v20, 0xbfb8aa3b, v196
	v_fmamk_f32 v21, v21, 0xbfb8aa3b, v197
	v_add_f32_dpp v176, v176, v176 quad_perm:[1,0,3,2] row_mask:0xf bank_mask:0xf bound_ctrl:1
	v_exp_f32_e32 v18, v18
	v_exp_f32_e32 v19, v19
	v_exp_f32_e32 v20, v20
	v_exp_f32_e32 v21, v21
	v_add_f32_dpp v176, v176, v176 quad_perm:[2,3,0,1] row_mask:0xf bank_mask:0xf bound_ctrl:1
	v_add_f32_e32 v18, 1.0, v18
	v_add_f32_e32 v19, 1.0, v19
	v_add_f32_e32 v20, 1.0, v20
	v_add_f32_e32 v21, 1.0, v21
	v_add_f32_dpp v176, v176, v176 row_half_mirror row_mask:0xf bank_mask:0xf bound_ctrl:1
	v_rcp_f32_e32 v18, v18
	v_rcp_f32_e32 v19, v19
	v_rcp_f32_e32 v20, v20
	v_rcp_f32_e32 v21, v21
	v_add_f32_dpp v176, v176, v176 row_mirror row_mask:0xf bank_mask:0xf bound_ctrl:1
	v_fmamk_f32 v14, v14, 0xbfb8aa3b, v190
	v_fmamk_f32 v15, v15, 0xbfb8aa3b, v191
	v_fmamk_f32 v16, v16, 0xbfb8aa3b, v192
	v_fmamk_f32 v17, v17, 0xbfb8aa3b, v193
	v_sqrt_f32_e32 v176, v176
	v_exp_f32_e32 v14, v14
	v_exp_f32_e32 v15, v15
	v_exp_f32_e32 v16, v16
	v_exp_f32_e32 v17, v17
	v_max_f32_e32 v176, 0x2b8cbccc, v176
	v_add_f32_e32 v14, 1.0, v14
	v_add_f32_e32 v15, 1.0, v15
	v_add_f32_e32 v16, 1.0, v16
	v_add_f32_e32 v17, 1.0, v17
	v_rcp_f32_e32 v178, v176
	v_rcp_f32_e32 v14, v14
	v_rcp_f32_e32 v15, v15
	v_rcp_f32_e32 v16, v16
	v_rcp_f32_e32 v17, v17
	v_mul_f32_e32 v14, 0xbf60028a, v14
	v_mul_f32_e32 v15, 0xbf60028a, v15
	v_mul_f32_e32 v16, 0xbf60028a, v16
	v_mul_f32_e32 v17, 0xbf60028a, v17
	v_exp_f32_e32 v14, v14
	v_exp_f32_e32 v15, v15
	v_exp_f32_e32 v16, v16
	v_exp_f32_e32 v17, v17
	v_add_f32_e32 v152, -1.0, v18
	v_add_f32_e32 v153, -1.0, v19
	v_add_f32_e32 v154, -1.0, v20
	v_add_f32_e32 v155, -1.0, v21
	v_fma_f32 v152, v202, v152, 1.0
	v_fma_f32 v153, v203, v153, 1.0
	v_fma_f32 v154, v204, v154, 1.0
	v_fma_f32 v155, v205, v155, 1.0
	v_mul_f32_e32 v152, v136, v152
	v_mul_f32_e32 v153, v238, v153
	v_mul_f32_e32 v154, v137, v154
	v_mul_f32_e32 v155, v239, v155
	v_mul_f32_e32 v156, v134, v152
	v_mul_f32_e32 v157, v236, v153
	v_mul_f32_e32 v158, v135, v154
	v_mul_f32_e32 v159, v237, v155
	v_mul_f32_e32 v177, v206, v156
	v_fmac_f32_e32 v177, v207, v157
	v_fmac_f32_e32 v177, v208, v158
	v_fmac_f32_e32 v177, v209, v159
	v_mul_f32_e32 v148, v148, v178
	v_mul_f32_e32 v149, v149, v178
	v_add_f32_dpp v177, v177, v177 quad_perm:[1,0,3,2] row_mask:0xf bank_mask:0xf bound_ctrl:1
	v_mul_f32_e32 v150, v150, v178
	v_mul_f32_e32 v151, v151, v178
	v_add_f32_dpp v177, v177, v177 quad_perm:[2,3,0,1] row_mask:0xf bank_mask:0xf bound_ctrl:1
	v_mul_f32_e32 v18, v18, v148
	v_mul_f32_e32 v19, v19, v149
	v_add_f32_dpp v177, v177, v177 row_half_mirror row_mask:0xf bank_mask:0xf bound_ctrl:1
	v_mul_f32_e32 v20, v20, v150
	v_mul_f32_e32 v21, v21, v151
	v_add_f32_dpp v177, v177, v177 row_mirror row_mask:0xf bank_mask:0xf bound_ctrl:1
	s_lshl_b32 s0, s57, 9
	s_add_u32 s62, s34, s0
	s_addc_u32 s63, s35, 0
	v_fmac_f32_e32 v146, v138, v177
	v_fmac_f32_e32 v248, v240, v177
	v_fmac_f32_e32 v147, v139, v177
	v_fmac_f32_e32 v249, v241, v177
	v_cvt_pk_bf16_f32 v72, v134, v236
	v_cvt_pk_bf16_f32 v73, v135, v237
	global_store_dwordx2 v250, v[72:73], s[62:63]
	v_cvt_pk_bf16_f32 v74, v14, v15
	v_cvt_pk_bf16_f32 v75, v16, v17
	s_add_u32 s0, s62, 0x500000
	s_addc_u32 s1, s63, 0
	global_store_dwordx2 v250, v[74:75], s[0:1]
	v_cvt_pk_bf16_f32 v180, v152, v153
	v_cvt_pk_bf16_f32 v181, v154, v155
	s_add_u32 s0, s62, 0xa00000
	s_addc_u32 s1, s63, 0
	global_store_dwordx2 v250, v[180:181], s[0:1]
	v_cvt_pk_bf16_f32 v72, v138, v240
	v_cvt_pk_bf16_f32 v73, v139, v241
	s_add_u32 s0, s62, 0xf00000
	s_addc_u32 s1, s63, 0
	global_store_dwordx2 v250, v[72:73], s[0:1]
	v_cvt_pk_bf16_f32 v74, v148, v149
	v_cvt_pk_bf16_f32 v75, v150, v151
	s_add_u32 s0, s62, 0x1400000
	s_addc_u32 s1, s63, 0
	global_store_dwordx2 v250, v[74:75], s[0:1]
	v_cvt_pk_bf16_f32 v180, v18, v19
	v_cvt_pk_bf16_f32 v181, v20, v21
	s_add_u32 s0, s62, 0x1900000
	s_addc_u32 s1, s63, 0
	global_store_dwordx2 v250, v[180:181], s[0:1]
	v_cvt_pk_bf16_f32 v72, v146, v248
	v_cvt_pk_bf16_f32 v73, v147, v249
	s_lshl_b32 s0, s57, 9
	s_add_u32 s0, s42, s0
	s_addc_u32 s1, s43, 0
	global_store_dwordx2 v250, v[72:73], s[0:1]
	s_branch .LBB0_476
